# convw: 16 transposing weight loads per tile batched into distinct registers with counted vmcnt drain (was load/wait/ds_write serialized)
# speedup vs baseline: 1.1638x; 1.0329x over previous
.LBB0_24:
	s_ashr_i32 s4, s13, 31
	s_lshr_b32 s4, s4, 28
	s_add_i32 s4, s13, s4
	s_ashr_i32 s14, s4, 4
	s_lshl_b32 s4, s14, 10
	s_lshl_b32 s5, s14, 6
	s_lshl_b32 s14, s14, 5
	v_or_b32_e32 v0, s5, v2
	s_andn2_b32 s14, s14, 63
	v_lshrrev_b32_e32 v0, 1, v0
	v_add_u32_e32 v1, s14, v6
	v_and_or_b32 v0, v0, 48, v1
	s_sub_i32 s4, s12, s4
	v_ashrrev_i32_e32 v1, 31, v0
	v_lshl_add_u64 v[0:1], v[0:1], 2, s[2:3]
	v_add_u32_e32 v11, s4, v3
	v_mad_i64_i32 v[12:13], s[14:15], v11, s74, v[0:1]
	s_barrier
	global_load_dword v30, v[12:13], off
	v_add_u32_e32 v26, s5, v4
	v_ashrrev_i32_e32 v27, 31, v26
	v_lshlrev_b64 v[26:27], 11, v[26:27]
	v_lshl_add_u64 v[26:27], s[16:17], 0, v[26:27]
	s_ashr_i32 s5, s4, 31
	v_lshl_add_u64 v[26:27], s[4:5], 1, v[26:27]
	v_lshl_add_u64 v[26:27], v[26:27], 0, v[200:201]
	s_add_i32 s13, s13, s33
	s_add_i32 s12, s12, s68
	s_cmpk_lt_i32 s13, 0x580
	v_add_u32_e32 v12, 4, v11
	v_mad_i64_i32 v[12:13], s[14:15], v12, s74, v[0:1]
	global_load_dword v31, v[12:13], off
	v_add_u32_e32 v12, 8, v11
	v_mad_i64_i32 v[12:13], s[14:15], v12, s74, v[0:1]
	global_load_dword v32, v[12:13], off
	v_add_u32_e32 v12, 12, v11
	v_mad_i64_i32 v[12:13], s[14:15], v12, s74, v[0:1]
	global_load_dword v33, v[12:13], off
	v_add_u32_e32 v12, 16, v11
	v_mad_i64_i32 v[12:13], s[14:15], v12, s74, v[0:1]
	global_load_dword v34, v[12:13], off
	v_add_u32_e32 v12, 20, v11
	v_mad_i64_i32 v[12:13], s[14:15], v12, s74, v[0:1]
	global_load_dword v35, v[12:13], off
	v_add_u32_e32 v12, 24, v11
	v_mad_i64_i32 v[12:13], s[14:15], v12, s74, v[0:1]
	global_load_dword v36, v[12:13], off
	v_add_u32_e32 v12, 28, v11
	v_mad_i64_i32 v[12:13], s[14:15], v12, s74, v[0:1]
	global_load_dword v37, v[12:13], off
	v_add_u32_e32 v12, 32, v11
	v_mad_i64_i32 v[12:13], s[14:15], v12, s74, v[0:1]
	global_load_dword v38, v[12:13], off
	v_add_u32_e32 v12, 36, v11
	v_mad_i64_i32 v[12:13], s[14:15], v12, s74, v[0:1]
	global_load_dword v39, v[12:13], off
	v_add_u32_e32 v12, 40, v11
	v_mad_i64_i32 v[12:13], s[14:15], v12, s74, v[0:1]
	global_load_dword v40, v[12:13], off
	v_add_u32_e32 v12, 44, v11
	v_mad_i64_i32 v[12:13], s[14:15], v12, s74, v[0:1]
	global_load_dword v41, v[12:13], off
	v_add_u32_e32 v12, 48, v11
	v_mad_i64_i32 v[12:13], s[14:15], v12, s74, v[0:1]
	global_load_dword v42, v[12:13], off
	v_add_u32_e32 v12, 52, v11
	v_mad_i64_i32 v[12:13], s[14:15], v12, s74, v[0:1]
	global_load_dword v43, v[12:13], off
	v_add_u32_e32 v12, 56, v11
	v_add_u32_e32 v11, 60, v11
	v_mad_i64_i32 v[12:13], s[14:15], v12, s74, v[0:1]
	v_mad_i64_i32 v[0:1], s[14:15], v11, s74, v[0:1]
	global_load_dword v44, v[12:13], off
	s_nop 0
	global_load_dword v45, v[0:1], off
	s_waitcnt vmcnt(15)
	ds_write_b32 v7, v30
	s_waitcnt vmcnt(14)
	ds_write_b32 v7, v31 offset:1040
	s_waitcnt vmcnt(13)
	ds_write_b32 v7, v32 offset:2080
	s_waitcnt vmcnt(12)
	ds_write_b32 v7, v33 offset:3120
	s_waitcnt vmcnt(11)
	ds_write_b32 v7, v34 offset:4160
	s_waitcnt vmcnt(10)
	ds_write_b32 v7, v35 offset:5200
	s_waitcnt vmcnt(9)
	ds_write_b32 v7, v36 offset:6240
	s_waitcnt vmcnt(8)
	ds_write_b32 v7, v37 offset:7280
	s_waitcnt vmcnt(7)
	ds_write_b32 v7, v38 offset:8320
	s_waitcnt vmcnt(6)
	ds_write_b32 v7, v39 offset:9360
	s_waitcnt vmcnt(5)
	ds_write_b32 v7, v40 offset:10400
	s_waitcnt vmcnt(4)
	ds_write_b32 v7, v41 offset:11440
	s_waitcnt vmcnt(3)
	ds_write_b32 v7, v42 offset:12480
	s_waitcnt vmcnt(2)
	ds_write_b32 v7, v43 offset:13520
	s_waitcnt vmcnt(1)
	ds_write_b32 v7, v44 offset:14560
	s_waitcnt vmcnt(0)
	ds_write_b32 v7, v45 offset:15600
	s_waitcnt lgkmcnt(0)
	s_barrier
	ds_read2_b32 v[0:1], v5 offset1:65
	ds_read2_b32 v[12:13], v5 offset0:130 offset1:195
	ds_read2_b32 v[14:15], v8 offset0:4 offset1:69
	ds_read2_b32 v[16:17], v8 offset0:134 offset1:199
	ds_read2_b32 v[18:19], v9 offset0:8 offset1:73
	ds_read2_b32 v[20:21], v9 offset0:138 offset1:203
	ds_read2_b32 v[22:23], v10 offset0:12 offset1:77
	ds_read2_b32 v[24:25], v10 offset0:142 offset1:207
	s_waitcnt lgkmcnt(6)
	v_and_b32_sdwa v11, v12, v232 dst_sel:DWORD dst_unused:UNUSED_PAD src0_sel:WORD_1 src1_sel:DWORD
	v_and_b32_sdwa v28, v0, v232 dst_sel:DWORD dst_unused:UNUSED_PAD src0_sel:WORD_1 src1_sel:DWORD
	v_add3_u32 v0, v0, v28, s69
	v_add3_u32 v11, v12, v11, s69
	v_and_b32_sdwa v12, v13, v232 dst_sel:DWORD dst_unused:UNUSED_PAD src0_sel:WORD_1 src1_sel:DWORD
	v_and_b32_sdwa v28, v1, v232 dst_sel:DWORD dst_unused:UNUSED_PAD src0_sel:WORD_1 src1_sel:DWORD
	v_add3_u32 v12, v13, v12, s69
	v_add3_u32 v1, v1, v28, s69
	v_and_b32_e32 v12, 0xffff0000, v12
	v_and_b32_e32 v1, 0xffff0000, v1
	v_or_b32_sdwa v13, v12, v11 dst_sel:DWORD dst_unused:UNUSED_PAD src0_sel:DWORD src1_sel:WORD_1
	v_or_b32_sdwa v12, v1, v0 dst_sel:DWORD dst_unused:UNUSED_PAD src0_sel:DWORD src1_sel:WORD_1
	s_waitcnt lgkmcnt(5)
	v_and_b32_sdwa v1, v14, v232 dst_sel:DWORD dst_unused:UNUSED_PAD src0_sel:WORD_1 src1_sel:DWORD
	v_add3_u32 v1, v14, v1, s69
	s_waitcnt lgkmcnt(4)
	v_and_b32_sdwa v11, v17, v232 dst_sel:DWORD dst_unused:UNUSED_PAD src0_sel:WORD_1 src1_sel:DWORD
	v_and_b32_sdwa v14, v15, v232 dst_sel:DWORD dst_unused:UNUSED_PAD src0_sel:WORD_1 src1_sel:DWORD
	v_and_b32_sdwa v0, v16, v232 dst_sel:DWORD dst_unused:UNUSED_PAD src0_sel:WORD_1 src1_sel:DWORD
	v_add3_u32 v11, v17, v11, s69
	v_add3_u32 v14, v15, v14, s69
	v_add3_u32 v0, v16, v0, s69
	v_and_b32_e32 v11, 0xffff0000, v11
	v_and_b32_e32 v14, 0xffff0000, v14
	v_or_b32_sdwa v15, v11, v0 dst_sel:DWORD dst_unused:UNUSED_PAD src0_sel:DWORD src1_sel:WORD_1
	v_or_b32_sdwa v14, v14, v1 dst_sel:DWORD dst_unused:UNUSED_PAD src0_sel:DWORD src1_sel:WORD_1
	s_waitcnt lgkmcnt(2)
	v_and_b32_sdwa v11, v21, v232 dst_sel:DWORD dst_unused:UNUSED_PAD src0_sel:WORD_1 src1_sel:DWORD
	global_store_dwordx4 v[26:27], v[12:15], off
	v_and_b32_sdwa v0, v20, v232 dst_sel:DWORD dst_unused:UNUSED_PAD src0_sel:WORD_1 src1_sel:DWORD
	v_add3_u32 v11, v21, v11, s69
	v_and_b32_sdwa v12, v19, v232 dst_sel:DWORD dst_unused:UNUSED_PAD src0_sel:WORD_1 src1_sel:DWORD
	v_and_b32_sdwa v1, v18, v232 dst_sel:DWORD dst_unused:UNUSED_PAD src0_sel:WORD_1 src1_sel:DWORD
	v_add3_u32 v0, v20, v0, s69
	v_add3_u32 v12, v19, v12, s69
	v_and_b32_e32 v11, 0xffff0000, v11
	v_add3_u32 v1, v18, v1, s69
	v_and_b32_e32 v12, 0xffff0000, v12
	v_or_b32_sdwa v13, v11, v0 dst_sel:DWORD dst_unused:UNUSED_PAD src0_sel:DWORD src1_sel:WORD_1
	s_waitcnt lgkmcnt(0)
	v_and_b32_sdwa v11, v25, v232 dst_sel:DWORD dst_unused:UNUSED_PAD src0_sel:WORD_1 src1_sel:DWORD
	v_and_b32_sdwa v14, v23, v232 dst_sel:DWORD dst_unused:UNUSED_PAD src0_sel:WORD_1 src1_sel:DWORD
	v_or_b32_sdwa v12, v12, v1 dst_sel:DWORD dst_unused:UNUSED_PAD src0_sel:DWORD src1_sel:WORD_1
	v_and_b32_sdwa v0, v24, v232 dst_sel:DWORD dst_unused:UNUSED_PAD src0_sel:WORD_1 src1_sel:DWORD
	v_and_b32_sdwa v1, v22, v232 dst_sel:DWORD dst_unused:UNUSED_PAD src0_sel:WORD_1 src1_sel:DWORD
	v_add3_u32 v11, v25, v11, s69
	v_add3_u32 v14, v23, v14, s69
	v_add3_u32 v1, v22, v1, s69
	v_add3_u32 v0, v24, v0, s69
	v_and_b32_e32 v11, 0xffff0000, v11
	v_and_b32_e32 v14, 0xffff0000, v14
	v_or_b32_sdwa v15, v11, v0 dst_sel:DWORD dst_unused:UNUSED_PAD src0_sel:DWORD src1_sel:WORD_1
	v_or_b32_sdwa v14, v14, v1 dst_sel:DWORD dst_unused:UNUSED_PAD src0_sel:DWORD src1_sel:WORD_1
	global_store_dwordx4 v[26:27], v[12:15], off offset:16
	s_cbranch_scc1 .LBB0_24

.LBB0_27:
	s_mul_hi_i32 s12, s15, 0x2e8ba2e9
	s_lshr_b32 s13, s12, 31
	s_ashr_i32 s12, s12, 3
	s_add_i32 s13, s12, s13
	s_mul_i32 s12, s13, 0xfffff500
	s_add_i32 s12, s14, s12
	s_lshl_b32 s13, s13, 6
	v_or_b32_e32 v0, s13, v8
	v_add_u32_e32 v2, s12, v9
	v_ashrrev_i32_e32 v1, 31, v0
	v_ashrrev_i32_e32 v3, 31, v2
	v_lshl_add_u64 v[0:1], v[0:1], 2, s[2:3]
	v_lshlrev_b64 v[4:5], 12, v[2:3]
	v_lshl_add_u64 v[4:5], v[0:1], 0, v[4:5]
	s_barrier
	global_load_dword v30, v[4:5], off
	v_add_u32_e32 v4, 4, v2
	v_ashrrev_i32_e32 v5, 31, v4
	v_lshlrev_b64 v[4:5], 12, v[4:5]
	v_lshl_add_u64 v[4:5], v[0:1], 0, v[4:5]
	v_add_u32_e32 v6, 0x400, v11
	v_add_u32_e32 v13, 0x800, v11
	v_mov_b64_e32 v[22:23], s[20:21]
	s_add_i32 s15, s15, s33
	s_add_i32 s14, s14, s68
	global_load_dword v31, v[4:5], off
	v_add_u32_e32 v4, 8, v2
	v_ashrrev_i32_e32 v5, 31, v4
	v_lshlrev_b64 v[4:5], 12, v[4:5]
	v_lshl_add_u64 v[4:5], v[0:1], 0, v[4:5]
	global_load_dword v32, v[4:5], off
	v_add_u32_e32 v4, 12, v2
	v_ashrrev_i32_e32 v5, 31, v4
	v_lshlrev_b64 v[4:5], 12, v[4:5]
	v_lshl_add_u64 v[4:5], v[0:1], 0, v[4:5]
	global_load_dword v33, v[4:5], off
	v_add_u32_e32 v4, 16, v2
	v_ashrrev_i32_e32 v5, 31, v4
	v_lshlrev_b64 v[4:5], 12, v[4:5]
	v_lshl_add_u64 v[4:5], v[0:1], 0, v[4:5]
	global_load_dword v34, v[4:5], off
	v_add_u32_e32 v4, 20, v2
	v_ashrrev_i32_e32 v5, 31, v4
	v_lshlrev_b64 v[4:5], 12, v[4:5]
	v_lshl_add_u64 v[4:5], v[0:1], 0, v[4:5]
	global_load_dword v35, v[4:5], off
	v_add_u32_e32 v4, 24, v2
	v_ashrrev_i32_e32 v5, 31, v4
	v_lshlrev_b64 v[4:5], 12, v[4:5]
	v_lshl_add_u64 v[4:5], v[0:1], 0, v[4:5]
	global_load_dword v36, v[4:5], off
	v_add_u32_e32 v4, 28, v2
	v_ashrrev_i32_e32 v5, 31, v4
	v_lshlrev_b64 v[4:5], 12, v[4:5]
	v_lshl_add_u64 v[4:5], v[0:1], 0, v[4:5]
	global_load_dword v37, v[4:5], off
	v_add_u32_e32 v4, 32, v2
	v_ashrrev_i32_e32 v5, 31, v4
	v_lshlrev_b64 v[4:5], 12, v[4:5]
	v_lshl_add_u64 v[4:5], v[0:1], 0, v[4:5]
	global_load_dword v38, v[4:5], off
	v_add_u32_e32 v4, 36, v2
	v_ashrrev_i32_e32 v5, 31, v4
	v_lshlrev_b64 v[4:5], 12, v[4:5]
	v_lshl_add_u64 v[4:5], v[0:1], 0, v[4:5]
	global_load_dword v39, v[4:5], off
	v_add_u32_e32 v4, 40, v2
	v_ashrrev_i32_e32 v5, 31, v4
	v_lshlrev_b64 v[4:5], 12, v[4:5]
	v_lshl_add_u64 v[4:5], v[0:1], 0, v[4:5]
	global_load_dword v40, v[4:5], off
	v_add_u32_e32 v4, 44, v2
	v_ashrrev_i32_e32 v5, 31, v4
	v_lshlrev_b64 v[4:5], 12, v[4:5]
	v_lshl_add_u64 v[4:5], v[0:1], 0, v[4:5]
	global_load_dword v41, v[4:5], off
	v_add_u32_e32 v4, 48, v2
	v_ashrrev_i32_e32 v5, 31, v4
	v_lshlrev_b64 v[4:5], 12, v[4:5]
	v_lshl_add_u64 v[4:5], v[0:1], 0, v[4:5]
	global_load_dword v42, v[4:5], off
	v_add_u32_e32 v4, 52, v2
	v_ashrrev_i32_e32 v5, 31, v4
	v_lshlrev_b64 v[4:5], 12, v[4:5]
	v_lshl_add_u64 v[4:5], v[0:1], 0, v[4:5]
	global_load_dword v43, v[4:5], off
	v_add_u32_e32 v4, 56, v2
	v_ashrrev_i32_e32 v5, 31, v4
	v_lshlrev_b64 v[4:5], 12, v[4:5]
	v_lshl_add_u64 v[4:5], v[0:1], 0, v[4:5]
	v_add_u32_e32 v2, 60, v2
	global_load_dword v44, v[4:5], off
	v_ashrrev_i32_e32 v3, 31, v2
	v_lshlrev_b64 v[2:3], 12, v[2:3]
	v_lshl_add_u64 v[0:1], v[0:1], 0, v[2:3]
	global_load_dword v45, v[0:1], off
	s_waitcnt vmcnt(15)
	ds_write_b32 v12, v30
	s_waitcnt vmcnt(14)
	ds_write_b32 v12, v31 offset:1040
	s_waitcnt vmcnt(13)
	ds_write_b32 v12, v32 offset:2080
	s_waitcnt vmcnt(12)
	ds_write_b32 v12, v33 offset:3120
	s_waitcnt vmcnt(11)
	ds_write_b32 v12, v34 offset:4160
	s_waitcnt vmcnt(10)
	ds_write_b32 v12, v35 offset:5200
	s_waitcnt vmcnt(9)
	ds_write_b32 v12, v36 offset:6240
	s_waitcnt vmcnt(8)
	ds_write_b32 v12, v37 offset:7280
	s_waitcnt vmcnt(7)
	ds_write_b32 v12, v38 offset:8320
	s_waitcnt vmcnt(6)
	ds_write_b32 v12, v39 offset:9360
	s_waitcnt vmcnt(5)
	ds_write_b32 v12, v40 offset:10400
	s_waitcnt vmcnt(4)
	ds_write_b32 v12, v41 offset:11440
	s_waitcnt vmcnt(3)
	ds_write_b32 v12, v42 offset:12480
	s_waitcnt vmcnt(2)
	ds_write_b32 v12, v43 offset:13520
	s_waitcnt vmcnt(1)
	ds_write_b32 v12, v44 offset:14560
	s_waitcnt vmcnt(0)
	ds_write_b32 v12, v45 offset:15600
	s_waitcnt lgkmcnt(0)
	s_barrier
	ds_read2_b32 v[0:1], v11 offset1:65
	ds_read2_b32 v[2:3], v11 offset0:130 offset1:195
	ds_read2_b32 v[4:5], v6 offset0:4 offset1:69
	ds_read2_b32 v[6:7], v6 offset0:134 offset1:199
	ds_read2_b32 v[14:15], v13 offset0:8 offset1:73
	ds_read2_b32 v[16:17], v13 offset0:138 offset1:203
	v_add_u32_e32 v13, 0xc00, v11
	ds_read2_b32 v[18:19], v13 offset0:12 offset1:77
	ds_read2_b32 v[20:21], v13 offset0:142 offset1:207
	v_add_u32_e32 v13, s13, v10
	v_mad_i64_i32 v[22:23], s[16:17], v13, s30, v[22:23]
	s_waitcnt lgkmcnt(6)
	v_and_b32_sdwa v13, v2, v232 dst_sel:DWORD dst_unused:UNUSED_PAD src0_sel:WORD_1 src1_sel:DWORD
	v_and_b32_sdwa v24, v0, v232 dst_sel:DWORD dst_unused:UNUSED_PAD src0_sel:WORD_1 src1_sel:DWORD
	v_add3_u32 v2, v2, v13, s69
	v_and_b32_sdwa v13, v3, v232 dst_sel:DWORD dst_unused:UNUSED_PAD src0_sel:WORD_1 src1_sel:DWORD
	v_add3_u32 v0, v0, v24, s69
	v_and_b32_sdwa v24, v1, v232 dst_sel:DWORD dst_unused:UNUSED_PAD src0_sel:WORD_1 src1_sel:DWORD
	v_add3_u32 v3, v3, v13, s69
	v_add3_u32 v1, v1, v24, s69
	v_and_b32_e32 v3, 0xffff0000, v3
	v_and_b32_e32 v13, 0xffff0000, v1
	v_or_b32_sdwa v1, v3, v2 dst_sel:DWORD dst_unused:UNUSED_PAD src0_sel:DWORD src1_sel:WORD_1
	s_waitcnt lgkmcnt(4)
	v_and_b32_sdwa v2, v6, v232 dst_sel:DWORD dst_unused:UNUSED_PAD src0_sel:WORD_1 src1_sel:DWORD
	v_and_b32_sdwa v3, v4, v232 dst_sel:DWORD dst_unused:UNUSED_PAD src0_sel:WORD_1 src1_sel:DWORD
	v_add3_u32 v4, v4, v3, s69
	v_add3_u32 v2, v6, v2, s69
	v_and_b32_sdwa v3, v7, v232 dst_sel:DWORD dst_unused:UNUSED_PAD src0_sel:WORD_1 src1_sel:DWORD
	v_and_b32_sdwa v6, v5, v232 dst_sel:DWORD dst_unused:UNUSED_PAD src0_sel:WORD_1 src1_sel:DWORD
	s_ashr_i32 s13, s12, 31
	v_add3_u32 v3, v7, v3, s69
	v_add3_u32 v5, v5, v6, s69
	v_lshl_add_u64 v[22:23], s[12:13], 1, v[22:23]
	v_and_b32_e32 v3, 0xffff0000, v3
	v_and_b32_e32 v5, 0xffff0000, v5
	v_lshl_add_u64 v[22:23], v[22:23], 0, v[200:201]
	v_or_b32_sdwa v0, v13, v0 dst_sel:DWORD dst_unused:UNUSED_PAD src0_sel:DWORD src1_sel:WORD_1
	v_or_b32_sdwa v3, v3, v2 dst_sel:DWORD dst_unused:UNUSED_PAD src0_sel:DWORD src1_sel:WORD_1
	v_or_b32_sdwa v2, v5, v4 dst_sel:DWORD dst_unused:UNUSED_PAD src0_sel:DWORD src1_sel:WORD_1
	global_store_dwordx4 v[22:23], v[0:3], off
	s_waitcnt lgkmcnt(1)
	v_and_b32_sdwa v5, v19, v232 dst_sel:DWORD dst_unused:UNUSED_PAD src0_sel:WORD_1 src1_sel:DWORD
	v_add3_u32 v5, v19, v5, s69
	v_and_b32_sdwa v1, v14, v232 dst_sel:DWORD dst_unused:UNUSED_PAD src0_sel:WORD_1 src1_sel:DWORD
	v_add3_u32 v2, v14, v1, s69
	v_and_b32_sdwa v1, v17, v232 dst_sel:DWORD dst_unused:UNUSED_PAD src0_sel:WORD_1 src1_sel:DWORD
	v_and_b32_sdwa v3, v15, v232 dst_sel:DWORD dst_unused:UNUSED_PAD src0_sel:WORD_1 src1_sel:DWORD
	v_and_b32_sdwa v0, v16, v232 dst_sel:DWORD dst_unused:UNUSED_PAD src0_sel:WORD_1 src1_sel:DWORD
	v_add3_u32 v1, v17, v1, s69
	v_add3_u32 v3, v15, v3, s69
	v_add3_u32 v0, v16, v0, s69
	v_and_b32_e32 v1, 0xffff0000, v1
	v_and_b32_e32 v3, 0xffff0000, v3
	v_or_b32_sdwa v1, v1, v0 dst_sel:DWORD dst_unused:UNUSED_PAD src0_sel:DWORD src1_sel:WORD_1
	v_or_b32_sdwa v0, v3, v2 dst_sel:DWORD dst_unused:UNUSED_PAD src0_sel:DWORD src1_sel:WORD_1
	v_and_b32_sdwa v3, v18, v232 dst_sel:DWORD dst_unused:UNUSED_PAD src0_sel:WORD_1 src1_sel:DWORD
	v_add3_u32 v4, v18, v3, s69
	s_waitcnt lgkmcnt(0)
	v_and_b32_sdwa v3, v21, v232 dst_sel:DWORD dst_unused:UNUSED_PAD src0_sel:WORD_1 src1_sel:DWORD
	v_and_b32_sdwa v2, v20, v232 dst_sel:DWORD dst_unused:UNUSED_PAD src0_sel:WORD_1 src1_sel:DWORD
	v_add3_u32 v3, v21, v3, s69
	v_add3_u32 v2, v20, v2, s69
	v_and_b32_e32 v3, 0xffff0000, v3
	v_and_b32_e32 v5, 0xffff0000, v5
	v_or_b32_sdwa v3, v3, v2 dst_sel:DWORD dst_unused:UNUSED_PAD src0_sel:DWORD src1_sel:WORD_1
	v_or_b32_sdwa v2, v5, v4 dst_sel:DWORD dst_unused:UNUSED_PAD src0_sel:DWORD src1_sel:WORD_1
	s_cmpk_lt_i32 s15, 0x2c0
	global_store_dwordx4 v[22:23], v[0:3], off offset:16
	s_cbranch_scc1 .LBB0_27

.LBB0_30:
	s_ashr_i32 s12, s15, 31
	s_lshr_b32 s12, s12, 28
	s_add_i32 s12, s15, s12
	s_ashr_i32 s13, s12, 4
	s_lshl_b32 s12, s13, 10
	s_lshl_b32 s13, s13, 6
	v_or_b32_e32 v0, s13, v4
	v_cmp_gt_i32_e32 vcc, s30, v0
	v_add_u32_e32 v1, 8, v0
	s_sub_i32 s12, s14, s12
	v_cndmask_b32_e32 v0, v1, v0, vcc
	v_ashrrev_i32_e32 v1, 31, v0
	v_lshl_add_u64 v[0:1], v[0:1], 2, s[2:3]
	v_add_u32_e32 v9, s12, v5
	v_mad_i64_i32 v[2:3], s[16:17], v9, s18, v[0:1]
	s_barrier
	global_load_dword v30, v[2:3], off
	v_add_u32_e32 v22, s13, v6
	v_ashrrev_i32_e32 v23, 31, v22
	v_lshlrev_b64 v[22:23], 11, v[22:23]
	v_lshl_add_u64 v[22:23], s[20:21], 0, v[22:23]
	s_ashr_i32 s13, s12, 31
	v_lshl_add_u64 v[22:23], s[12:13], 1, v[22:23]
	v_lshl_add_u64 v[22:23], v[22:23], 0, v[200:201]
	s_add_i32 s15, s15, s33
	s_add_i32 s14, s14, s68
	s_cmpk_lt_i32 s15, 0x240
	v_add_u32_e32 v2, 4, v9
	v_mad_i64_i32 v[2:3], s[16:17], v2, s18, v[0:1]
	global_load_dword v31, v[2:3], off
	v_add_u32_e32 v2, 8, v9
	v_mad_i64_i32 v[2:3], s[16:17], v2, s18, v[0:1]
	global_load_dword v32, v[2:3], off
	v_add_u32_e32 v2, 12, v9
	v_mad_i64_i32 v[2:3], s[16:17], v2, s18, v[0:1]
	global_load_dword v33, v[2:3], off
	v_add_u32_e32 v2, 16, v9
	v_mad_i64_i32 v[2:3], s[16:17], v2, s18, v[0:1]
	global_load_dword v34, v[2:3], off
	v_add_u32_e32 v2, 20, v9
	v_mad_i64_i32 v[2:3], s[16:17], v2, s18, v[0:1]
	global_load_dword v35, v[2:3], off
	v_add_u32_e32 v2, 24, v9
	v_mad_i64_i32 v[2:3], s[16:17], v2, s18, v[0:1]
	global_load_dword v36, v[2:3], off
	v_add_u32_e32 v2, 28, v9
	v_mad_i64_i32 v[2:3], s[16:17], v2, s18, v[0:1]
	global_load_dword v37, v[2:3], off
	v_add_u32_e32 v2, 32, v9
	v_mad_i64_i32 v[2:3], s[16:17], v2, s18, v[0:1]
	global_load_dword v38, v[2:3], off
	v_add_u32_e32 v2, 36, v9
	v_mad_i64_i32 v[2:3], s[16:17], v2, s18, v[0:1]
	global_load_dword v39, v[2:3], off
	v_add_u32_e32 v2, 40, v9
	v_mad_i64_i32 v[2:3], s[16:17], v2, s18, v[0:1]
	global_load_dword v40, v[2:3], off
	v_add_u32_e32 v2, 44, v9
	v_mad_i64_i32 v[2:3], s[16:17], v2, s18, v[0:1]
	global_load_dword v41, v[2:3], off
	v_add_u32_e32 v2, 48, v9
	v_mad_i64_i32 v[2:3], s[16:17], v2, s18, v[0:1]
	global_load_dword v42, v[2:3], off
	v_add_u32_e32 v2, 52, v9
	v_mad_i64_i32 v[2:3], s[16:17], v2, s18, v[0:1]
	global_load_dword v43, v[2:3], off
	v_add_u32_e32 v2, 56, v9
	v_mad_i64_i32 v[2:3], s[16:17], v2, s18, v[0:1]
	global_load_dword v44, v[2:3], off
	v_add_u32_e32 v2, 60, v9
	v_mad_i64_i32 v[0:1], s[16:17], v2, s18, v[0:1]
	global_load_dword v45, v[0:1], off
	v_add_u32_e32 v9, 0x400, v7
	s_waitcnt vmcnt(15)
	ds_write_b32 v8, v30
	s_waitcnt vmcnt(14)
	ds_write_b32 v8, v31 offset:1040
	s_waitcnt vmcnt(13)
	ds_write_b32 v8, v32 offset:2080
	s_waitcnt vmcnt(12)
	ds_write_b32 v8, v33 offset:3120
	s_waitcnt vmcnt(11)
	ds_write_b32 v8, v34 offset:4160
	s_waitcnt vmcnt(10)
	ds_write_b32 v8, v35 offset:5200
	s_waitcnt vmcnt(9)
	ds_write_b32 v8, v36 offset:6240
	s_waitcnt vmcnt(8)
	ds_write_b32 v8, v37 offset:7280
	s_waitcnt vmcnt(7)
	ds_write_b32 v8, v38 offset:8320
	s_waitcnt vmcnt(6)
	ds_write_b32 v8, v39 offset:9360
	s_waitcnt vmcnt(5)
	ds_write_b32 v8, v40 offset:10400
	s_waitcnt vmcnt(4)
	ds_write_b32 v8, v41 offset:11440
	s_waitcnt vmcnt(3)
	ds_write_b32 v8, v42 offset:12480
	s_waitcnt vmcnt(2)
	ds_write_b32 v8, v43 offset:13520
	s_waitcnt vmcnt(1)
	ds_write_b32 v8, v44 offset:14560
	s_waitcnt vmcnt(0)
	ds_write_b32 v8, v45 offset:15600
	s_waitcnt lgkmcnt(0)
	s_barrier
	ds_read2_b32 v[0:1], v7 offset1:65
	ds_read2_b32 v[2:3], v7 offset0:130 offset1:195
	ds_read2_b32 v[10:11], v9 offset0:4 offset1:69
	ds_read2_b32 v[12:13], v9 offset0:134 offset1:199
	v_add_u32_e32 v9, 0x800, v7
	ds_read2_b32 v[14:15], v9 offset0:8 offset1:73
	ds_read2_b32 v[16:17], v9 offset0:138 offset1:203
	v_add_u32_e32 v9, 0xc00, v7
	ds_read2_b32 v[18:19], v9 offset0:12 offset1:77
	ds_read2_b32 v[20:21], v9 offset0:142 offset1:207
	s_waitcnt lgkmcnt(6)
	v_and_b32_sdwa v9, v2, v232 dst_sel:DWORD dst_unused:UNUSED_PAD src0_sel:WORD_1 src1_sel:DWORD
	v_and_b32_sdwa v24, v0, v232 dst_sel:DWORD dst_unused:UNUSED_PAD src0_sel:WORD_1 src1_sel:DWORD
	v_add3_u32 v2, v2, v9, s69
	v_and_b32_sdwa v9, v3, v232 dst_sel:DWORD dst_unused:UNUSED_PAD src0_sel:WORD_1 src1_sel:DWORD
	v_add3_u32 v0, v0, v24, s69
	v_and_b32_sdwa v24, v1, v232 dst_sel:DWORD dst_unused:UNUSED_PAD src0_sel:WORD_1 src1_sel:DWORD
	v_add3_u32 v3, v3, v9, s69
	v_add3_u32 v1, v1, v24, s69
	v_and_b32_e32 v3, 0xffff0000, v3
	v_and_b32_e32 v9, 0xffff0000, v1
	v_or_b32_sdwa v1, v3, v2 dst_sel:DWORD dst_unused:UNUSED_PAD src0_sel:DWORD src1_sel:WORD_1
	s_waitcnt lgkmcnt(5)
	v_and_b32_sdwa v3, v10, v232 dst_sel:DWORD dst_unused:UNUSED_PAD src0_sel:WORD_1 src1_sel:DWORD
	v_or_b32_sdwa v0, v9, v0 dst_sel:DWORD dst_unused:UNUSED_PAD src0_sel:DWORD src1_sel:WORD_1
	v_add3_u32 v9, v10, v3, s69
	s_waitcnt lgkmcnt(4)
	v_and_b32_sdwa v3, v13, v232 dst_sel:DWORD dst_unused:UNUSED_PAD src0_sel:WORD_1 src1_sel:DWORD
	v_and_b32_sdwa v10, v11, v232 dst_sel:DWORD dst_unused:UNUSED_PAD src0_sel:WORD_1 src1_sel:DWORD
	v_and_b32_sdwa v2, v12, v232 dst_sel:DWORD dst_unused:UNUSED_PAD src0_sel:WORD_1 src1_sel:DWORD
	v_add3_u32 v3, v13, v3, s69
	v_add3_u32 v10, v11, v10, s69
	v_add3_u32 v2, v12, v2, s69
	v_and_b32_e32 v3, 0xffff0000, v3
	v_and_b32_e32 v10, 0xffff0000, v10
	v_or_b32_sdwa v3, v3, v2 dst_sel:DWORD dst_unused:UNUSED_PAD src0_sel:DWORD src1_sel:WORD_1
	v_or_b32_sdwa v2, v10, v9 dst_sel:DWORD dst_unused:UNUSED_PAD src0_sel:DWORD src1_sel:WORD_1
	global_store_dwordx4 v[22:23], v[0:3], off
	s_waitcnt lgkmcnt(1)
	v_and_b32_sdwa v10, v19, v232 dst_sel:DWORD dst_unused:UNUSED_PAD src0_sel:WORD_1 src1_sel:DWORD
	v_add3_u32 v10, v19, v10, s69
	v_and_b32_sdwa v1, v14, v232 dst_sel:DWORD dst_unused:UNUSED_PAD src0_sel:WORD_1 src1_sel:DWORD
	v_add3_u32 v2, v14, v1, s69
	v_and_b32_sdwa v1, v17, v232 dst_sel:DWORD dst_unused:UNUSED_PAD src0_sel:WORD_1 src1_sel:DWORD
	v_and_b32_sdwa v3, v15, v232 dst_sel:DWORD dst_unused:UNUSED_PAD src0_sel:WORD_1 src1_sel:DWORD
	v_and_b32_sdwa v0, v16, v232 dst_sel:DWORD dst_unused:UNUSED_PAD src0_sel:WORD_1 src1_sel:DWORD
	v_add3_u32 v1, v17, v1, s69
	v_add3_u32 v3, v15, v3, s69
	v_add3_u32 v0, v16, v0, s69
	v_and_b32_e32 v1, 0xffff0000, v1
	v_and_b32_e32 v3, 0xffff0000, v3
	v_or_b32_sdwa v1, v1, v0 dst_sel:DWORD dst_unused:UNUSED_PAD src0_sel:DWORD src1_sel:WORD_1
	v_or_b32_sdwa v0, v3, v2 dst_sel:DWORD dst_unused:UNUSED_PAD src0_sel:DWORD src1_sel:WORD_1
	v_and_b32_sdwa v3, v18, v232 dst_sel:DWORD dst_unused:UNUSED_PAD src0_sel:WORD_1 src1_sel:DWORD
	v_add3_u32 v9, v18, v3, s69
	s_waitcnt lgkmcnt(0)
	v_and_b32_sdwa v3, v21, v232 dst_sel:DWORD dst_unused:UNUSED_PAD src0_sel:WORD_1 src1_sel:DWORD
	v_and_b32_sdwa v2, v20, v232 dst_sel:DWORD dst_unused:UNUSED_PAD src0_sel:WORD_1 src1_sel:DWORD
	v_add3_u32 v3, v21, v3, s69
	v_add3_u32 v2, v20, v2, s69
	v_and_b32_e32 v3, 0xffff0000, v3
	v_and_b32_e32 v10, 0xffff0000, v10
	v_or_b32_sdwa v3, v3, v2 dst_sel:DWORD dst_unused:UNUSED_PAD src0_sel:DWORD src1_sel:WORD_1
	v_or_b32_sdwa v2, v10, v9 dst_sel:DWORD dst_unused:UNUSED_PAD src0_sel:DWORD src1_sel:WORD_1
	global_store_dwordx4 v[22:23], v[0:3], off offset:16
	s_cbranch_scc1 .LBB0_30

.LBB0_33:
	s_ashr_i32 s12, s15, 31
	s_lshr_b32 s12, s12, 28
	s_add_i32 s12, s15, s12
	s_ashr_i32 s13, s12, 4
	s_lshl_b32 s12, s13, 10
	s_lshl_b32 s13, s13, 6
	v_or_b32_e32 v0, s13, v4
	v_ashrrev_i32_e32 v1, 31, v0
	s_sub_i32 s12, s14, s12
	v_lshl_add_u64 v[0:1], v[0:1], 2, s[2:3]
	s_mov_b64 s[16:17], 0x2420
	v_lshl_add_u64 v[0:1], v[0:1], 0, s[16:17]
	v_add_u32_e32 v9, s12, v5
	v_mad_i64_i32 v[2:3], s[16:17], v9, s18, v[0:1]
	s_barrier
	global_load_dword v30, v[2:3], off
	v_add_u32_e32 v22, s13, v6
	v_ashrrev_i32_e32 v23, 31, v22
	v_lshlrev_b64 v[22:23], 11, v[22:23]
	v_lshl_add_u64 v[22:23], s[20:21], 0, v[22:23]
	s_ashr_i32 s13, s12, 31
	v_lshl_add_u64 v[22:23], s[12:13], 1, v[22:23]
	v_lshl_add_u64 v[22:23], v[22:23], 0, v[200:201]
	s_add_i32 s15, s15, s33
	s_add_i32 s14, s14, s68
	s_cmpk_lt_i32 s15, 0x400
	v_add_u32_e32 v2, 4, v9
	v_mad_i64_i32 v[2:3], s[16:17], v2, s18, v[0:1]
	global_load_dword v31, v[2:3], off
	v_add_u32_e32 v2, 8, v9
	v_mad_i64_i32 v[2:3], s[16:17], v2, s18, v[0:1]
	global_load_dword v32, v[2:3], off
	v_add_u32_e32 v2, 12, v9
	v_mad_i64_i32 v[2:3], s[16:17], v2, s18, v[0:1]
	global_load_dword v33, v[2:3], off
	v_add_u32_e32 v2, 16, v9
	v_mad_i64_i32 v[2:3], s[16:17], v2, s18, v[0:1]
	global_load_dword v34, v[2:3], off
	v_add_u32_e32 v2, 20, v9
	v_mad_i64_i32 v[2:3], s[16:17], v2, s18, v[0:1]
	global_load_dword v35, v[2:3], off
	v_add_u32_e32 v2, 24, v9
	v_mad_i64_i32 v[2:3], s[16:17], v2, s18, v[0:1]
	global_load_dword v36, v[2:3], off
	v_add_u32_e32 v2, 28, v9
	v_mad_i64_i32 v[2:3], s[16:17], v2, s18, v[0:1]
	global_load_dword v37, v[2:3], off
	v_add_u32_e32 v2, 32, v9
	v_mad_i64_i32 v[2:3], s[16:17], v2, s18, v[0:1]
	global_load_dword v38, v[2:3], off
	v_add_u32_e32 v2, 36, v9
	v_mad_i64_i32 v[2:3], s[16:17], v2, s18, v[0:1]
	global_load_dword v39, v[2:3], off
	v_add_u32_e32 v2, 40, v9
	v_mad_i64_i32 v[2:3], s[16:17], v2, s18, v[0:1]
	global_load_dword v40, v[2:3], off
	v_add_u32_e32 v2, 44, v9
	v_mad_i64_i32 v[2:3], s[16:17], v2, s18, v[0:1]
	global_load_dword v41, v[2:3], off
	v_add_u32_e32 v2, 48, v9
	v_mad_i64_i32 v[2:3], s[16:17], v2, s18, v[0:1]
	global_load_dword v42, v[2:3], off
	v_add_u32_e32 v2, 52, v9
	v_mad_i64_i32 v[2:3], s[16:17], v2, s18, v[0:1]
	global_load_dword v43, v[2:3], off
	v_add_u32_e32 v2, 56, v9
	v_mad_i64_i32 v[2:3], s[16:17], v2, s18, v[0:1]
	global_load_dword v44, v[2:3], off
	v_add_u32_e32 v2, 60, v9
	v_mad_i64_i32 v[0:1], s[16:17], v2, s18, v[0:1]
	global_load_dword v45, v[0:1], off
	v_add_u32_e32 v9, 0x400, v7
	s_waitcnt vmcnt(15)
	ds_write_b32 v8, v30
	s_waitcnt vmcnt(14)
	ds_write_b32 v8, v31 offset:1040
	s_waitcnt vmcnt(13)
	ds_write_b32 v8, v32 offset:2080
	s_waitcnt vmcnt(12)
	ds_write_b32 v8, v33 offset:3120
	s_waitcnt vmcnt(11)
	ds_write_b32 v8, v34 offset:4160
	s_waitcnt vmcnt(10)
	ds_write_b32 v8, v35 offset:5200
	s_waitcnt vmcnt(9)
	ds_write_b32 v8, v36 offset:6240
	s_waitcnt vmcnt(8)
	ds_write_b32 v8, v37 offset:7280
	s_waitcnt vmcnt(7)
	ds_write_b32 v8, v38 offset:8320
	s_waitcnt vmcnt(6)
	ds_write_b32 v8, v39 offset:9360
	s_waitcnt vmcnt(5)
	ds_write_b32 v8, v40 offset:10400
	s_waitcnt vmcnt(4)
	ds_write_b32 v8, v41 offset:11440
	s_waitcnt vmcnt(3)
	ds_write_b32 v8, v42 offset:12480
	s_waitcnt vmcnt(2)
	ds_write_b32 v8, v43 offset:13520
	s_waitcnt vmcnt(1)
	ds_write_b32 v8, v44 offset:14560
	s_waitcnt vmcnt(0)
	ds_write_b32 v8, v45 offset:15600
	s_waitcnt lgkmcnt(0)
	s_barrier
	ds_read2_b32 v[0:1], v7 offset1:65
	ds_read2_b32 v[2:3], v7 offset0:130 offset1:195
	ds_read2_b32 v[10:11], v9 offset0:4 offset1:69
	ds_read2_b32 v[12:13], v9 offset0:134 offset1:199
	v_add_u32_e32 v9, 0x800, v7
	ds_read2_b32 v[14:15], v9 offset0:8 offset1:73
	ds_read2_b32 v[16:17], v9 offset0:138 offset1:203
	v_add_u32_e32 v9, 0xc00, v7
	ds_read2_b32 v[18:19], v9 offset0:12 offset1:77
	ds_read2_b32 v[20:21], v9 offset0:142 offset1:207
	s_waitcnt lgkmcnt(6)
	v_and_b32_sdwa v9, v2, v232 dst_sel:DWORD dst_unused:UNUSED_PAD src0_sel:WORD_1 src1_sel:DWORD
	v_and_b32_sdwa v24, v0, v232 dst_sel:DWORD dst_unused:UNUSED_PAD src0_sel:WORD_1 src1_sel:DWORD
	v_add3_u32 v2, v2, v9, s69
	v_and_b32_sdwa v9, v3, v232 dst_sel:DWORD dst_unused:UNUSED_PAD src0_sel:WORD_1 src1_sel:DWORD
	v_add3_u32 v0, v0, v24, s69
	v_and_b32_sdwa v24, v1, v232 dst_sel:DWORD dst_unused:UNUSED_PAD src0_sel:WORD_1 src1_sel:DWORD
	v_add3_u32 v3, v3, v9, s69
	v_add3_u32 v1, v1, v24, s69
	v_and_b32_e32 v3, 0xffff0000, v3
	v_and_b32_e32 v9, 0xffff0000, v1
	v_or_b32_sdwa v1, v3, v2 dst_sel:DWORD dst_unused:UNUSED_PAD src0_sel:DWORD src1_sel:WORD_1
	s_waitcnt lgkmcnt(5)
	v_and_b32_sdwa v3, v10, v232 dst_sel:DWORD dst_unused:UNUSED_PAD src0_sel:WORD_1 src1_sel:DWORD
	v_or_b32_sdwa v0, v9, v0 dst_sel:DWORD dst_unused:UNUSED_PAD src0_sel:DWORD src1_sel:WORD_1
	v_add3_u32 v9, v10, v3, s69
	s_waitcnt lgkmcnt(4)
	v_and_b32_sdwa v3, v13, v232 dst_sel:DWORD dst_unused:UNUSED_PAD src0_sel:WORD_1 src1_sel:DWORD
	v_and_b32_sdwa v10, v11, v232 dst_sel:DWORD dst_unused:UNUSED_PAD src0_sel:WORD_1 src1_sel:DWORD
	v_and_b32_sdwa v2, v12, v232 dst_sel:DWORD dst_unused:UNUSED_PAD src0_sel:WORD_1 src1_sel:DWORD
	v_add3_u32 v3, v13, v3, s69
	v_add3_u32 v10, v11, v10, s69
	v_add3_u32 v2, v12, v2, s69
	v_and_b32_e32 v3, 0xffff0000, v3
	v_and_b32_e32 v10, 0xffff0000, v10
	v_or_b32_sdwa v3, v3, v2 dst_sel:DWORD dst_unused:UNUSED_PAD src0_sel:DWORD src1_sel:WORD_1
	v_or_b32_sdwa v2, v10, v9 dst_sel:DWORD dst_unused:UNUSED_PAD src0_sel:DWORD src1_sel:WORD_1
	global_store_dwordx4 v[22:23], v[0:3], off
	s_waitcnt lgkmcnt(1)
	v_and_b32_sdwa v10, v19, v232 dst_sel:DWORD dst_unused:UNUSED_PAD src0_sel:WORD_1 src1_sel:DWORD
	v_add3_u32 v10, v19, v10, s69
	v_and_b32_sdwa v1, v14, v232 dst_sel:DWORD dst_unused:UNUSED_PAD src0_sel:WORD_1 src1_sel:DWORD
	v_add3_u32 v2, v14, v1, s69
	v_and_b32_sdwa v1, v17, v232 dst_sel:DWORD dst_unused:UNUSED_PAD src0_sel:WORD_1 src1_sel:DWORD
	v_and_b32_sdwa v3, v15, v232 dst_sel:DWORD dst_unused:UNUSED_PAD src0_sel:WORD_1 src1_sel:DWORD
	v_and_b32_sdwa v0, v16, v232 dst_sel:DWORD dst_unused:UNUSED_PAD src0_sel:WORD_1 src1_sel:DWORD
	v_add3_u32 v1, v17, v1, s69
	v_add3_u32 v3, v15, v3, s69
	v_add3_u32 v0, v16, v0, s69
	v_and_b32_e32 v1, 0xffff0000, v1
	v_and_b32_e32 v3, 0xffff0000, v3
	v_or_b32_sdwa v1, v1, v0 dst_sel:DWORD dst_unused:UNUSED_PAD src0_sel:DWORD src1_sel:WORD_1
	v_or_b32_sdwa v0, v3, v2 dst_sel:DWORD dst_unused:UNUSED_PAD src0_sel:DWORD src1_sel:WORD_1
	v_and_b32_sdwa v3, v18, v232 dst_sel:DWORD dst_unused:UNUSED_PAD src0_sel:WORD_1 src1_sel:DWORD
	v_add3_u32 v9, v18, v3, s69
	s_waitcnt lgkmcnt(0)
	v_and_b32_sdwa v3, v21, v232 dst_sel:DWORD dst_unused:UNUSED_PAD src0_sel:WORD_1 src1_sel:DWORD
	v_and_b32_sdwa v2, v20, v232 dst_sel:DWORD dst_unused:UNUSED_PAD src0_sel:WORD_1 src1_sel:DWORD
	v_add3_u32 v3, v21, v3, s69
	v_add3_u32 v2, v20, v2, s69
	v_and_b32_e32 v3, 0xffff0000, v3
	v_and_b32_e32 v10, 0xffff0000, v10
	v_or_b32_sdwa v3, v3, v2 dst_sel:DWORD dst_unused:UNUSED_PAD src0_sel:DWORD src1_sel:WORD_1
	v_or_b32_sdwa v2, v10, v9 dst_sel:DWORD dst_unused:UNUSED_PAD src0_sel:DWORD src1_sel:WORD_1
	global_store_dwordx4 v[22:23], v[0:3], off offset:16
	s_cbranch_scc1 .LBB0_33

.LBB0_38:
	s_ashr_i32 s14, s21, 31
	s_lshr_b32 s14, s14, 30
	s_add_i32 s14, s21, s14
	s_ashr_i32 s15, s14, 2
	s_lshl_b32 s14, s15, 8
	s_sub_i32 s14, s30, s14
	s_lshl_b32 s15, s15, 6
	v_or_b32_e32 v0, s15, v8
	v_add_u32_e32 v2, s14, v9
	v_ashrrev_i32_e32 v1, 31, v0
	v_ashrrev_i32_e32 v3, 31, v2
	v_lshl_add_u64 v[0:1], v[0:1], 2, s[2:3]
	v_lshlrev_b64 v[4:5], 12, v[2:3]
	v_lshl_add_u64 v[4:5], v[0:1], 0, v[4:5]
	s_barrier
	global_load_dword v30, v[4:5], off
	v_add_u32_e32 v4, 4, v2
	v_ashrrev_i32_e32 v5, 31, v4
	v_lshlrev_b64 v[4:5], 12, v[4:5]
	v_lshl_add_u64 v[4:5], v[0:1], 0, v[4:5]
	v_add_u32_e32 v6, 0x400, v11
	v_add_u32_e32 v13, 0x800, v11
	v_add_u32_e32 v22, s15, v10
	v_ashrrev_i32_e32 v23, 31, v22
	v_lshlrev_b64 v[22:23], 9, v[22:23]
	v_lshl_add_u64 v[22:23], s[12:13], 0, v[22:23]
	s_ashr_i32 s15, s14, 31
	v_lshl_add_u64 v[22:23], s[14:15], 1, v[22:23]
	v_lshl_add_u64 v[22:23], v[22:23], 0, v[200:201]
	s_add_i32 s21, s21, s33
	s_add_i32 s30, s30, s68
	s_cmp_lt_i32 s21, 64
	global_load_dword v31, v[4:5], off
	v_add_u32_e32 v4, 8, v2
	v_ashrrev_i32_e32 v5, 31, v4
	v_lshlrev_b64 v[4:5], 12, v[4:5]
	v_lshl_add_u64 v[4:5], v[0:1], 0, v[4:5]
	global_load_dword v32, v[4:5], off
	v_add_u32_e32 v4, 12, v2
	v_ashrrev_i32_e32 v5, 31, v4
	v_lshlrev_b64 v[4:5], 12, v[4:5]
	v_lshl_add_u64 v[4:5], v[0:1], 0, v[4:5]
	global_load_dword v33, v[4:5], off
	v_add_u32_e32 v4, 16, v2
	v_ashrrev_i32_e32 v5, 31, v4
	v_lshlrev_b64 v[4:5], 12, v[4:5]
	v_lshl_add_u64 v[4:5], v[0:1], 0, v[4:5]
	global_load_dword v34, v[4:5], off
	v_add_u32_e32 v4, 20, v2
	v_ashrrev_i32_e32 v5, 31, v4
	v_lshlrev_b64 v[4:5], 12, v[4:5]
	v_lshl_add_u64 v[4:5], v[0:1], 0, v[4:5]
	global_load_dword v35, v[4:5], off
	v_add_u32_e32 v4, 24, v2
	v_ashrrev_i32_e32 v5, 31, v4
	v_lshlrev_b64 v[4:5], 12, v[4:5]
	v_lshl_add_u64 v[4:5], v[0:1], 0, v[4:5]
	global_load_dword v36, v[4:5], off
	v_add_u32_e32 v4, 28, v2
	v_ashrrev_i32_e32 v5, 31, v4
	v_lshlrev_b64 v[4:5], 12, v[4:5]
	v_lshl_add_u64 v[4:5], v[0:1], 0, v[4:5]
	global_load_dword v37, v[4:5], off
	v_add_u32_e32 v4, 32, v2
	v_ashrrev_i32_e32 v5, 31, v4
	v_lshlrev_b64 v[4:5], 12, v[4:5]
	v_lshl_add_u64 v[4:5], v[0:1], 0, v[4:5]
	global_load_dword v38, v[4:5], off
	v_add_u32_e32 v4, 36, v2
	v_ashrrev_i32_e32 v5, 31, v4
	v_lshlrev_b64 v[4:5], 12, v[4:5]
	v_lshl_add_u64 v[4:5], v[0:1], 0, v[4:5]
	global_load_dword v39, v[4:5], off
	v_add_u32_e32 v4, 40, v2
	v_ashrrev_i32_e32 v5, 31, v4
	v_lshlrev_b64 v[4:5], 12, v[4:5]
	v_lshl_add_u64 v[4:5], v[0:1], 0, v[4:5]
	global_load_dword v40, v[4:5], off
	v_add_u32_e32 v4, 44, v2
	v_ashrrev_i32_e32 v5, 31, v4
	v_lshlrev_b64 v[4:5], 12, v[4:5]
	v_lshl_add_u64 v[4:5], v[0:1], 0, v[4:5]
	global_load_dword v41, v[4:5], off
	v_add_u32_e32 v4, 48, v2
	v_ashrrev_i32_e32 v5, 31, v4
	v_lshlrev_b64 v[4:5], 12, v[4:5]
	v_lshl_add_u64 v[4:5], v[0:1], 0, v[4:5]
	global_load_dword v42, v[4:5], off
	v_add_u32_e32 v4, 52, v2
	v_ashrrev_i32_e32 v5, 31, v4
	v_lshlrev_b64 v[4:5], 12, v[4:5]
	v_lshl_add_u64 v[4:5], v[0:1], 0, v[4:5]
	global_load_dword v43, v[4:5], off
	v_add_u32_e32 v4, 56, v2
	v_ashrrev_i32_e32 v5, 31, v4
	v_lshlrev_b64 v[4:5], 12, v[4:5]
	v_lshl_add_u64 v[4:5], v[0:1], 0, v[4:5]
	v_add_u32_e32 v2, 60, v2
	global_load_dword v44, v[4:5], off
	v_ashrrev_i32_e32 v3, 31, v2
	v_lshlrev_b64 v[2:3], 12, v[2:3]
	v_lshl_add_u64 v[0:1], v[0:1], 0, v[2:3]
	global_load_dword v45, v[0:1], off
	s_waitcnt vmcnt(15)
	ds_write_b32 v12, v30
	s_waitcnt vmcnt(14)
	ds_write_b32 v12, v31 offset:1040
	s_waitcnt vmcnt(13)
	ds_write_b32 v12, v32 offset:2080
	s_waitcnt vmcnt(12)
	ds_write_b32 v12, v33 offset:3120
	s_waitcnt vmcnt(11)
	ds_write_b32 v12, v34 offset:4160
	s_waitcnt vmcnt(10)
	ds_write_b32 v12, v35 offset:5200
	s_waitcnt vmcnt(9)
	ds_write_b32 v12, v36 offset:6240
	s_waitcnt vmcnt(8)
	ds_write_b32 v12, v37 offset:7280
	s_waitcnt vmcnt(7)
	ds_write_b32 v12, v38 offset:8320
	s_waitcnt vmcnt(6)
	ds_write_b32 v12, v39 offset:9360
	s_waitcnt vmcnt(5)
	ds_write_b32 v12, v40 offset:10400
	s_waitcnt vmcnt(4)
	ds_write_b32 v12, v41 offset:11440
	s_waitcnt vmcnt(3)
	ds_write_b32 v12, v42 offset:12480
	s_waitcnt vmcnt(2)
	ds_write_b32 v12, v43 offset:13520
	s_waitcnt vmcnt(1)
	ds_write_b32 v12, v44 offset:14560
	s_waitcnt vmcnt(0)
	ds_write_b32 v12, v45 offset:15600
	s_waitcnt lgkmcnt(0)
	s_barrier
	ds_read2_b32 v[0:1], v11 offset1:65
	ds_read2_b32 v[2:3], v11 offset0:130 offset1:195
	ds_read2_b32 v[4:5], v6 offset0:4 offset1:69
	ds_read2_b32 v[6:7], v6 offset0:134 offset1:199
	ds_read2_b32 v[14:15], v13 offset0:8 offset1:73
	ds_read2_b32 v[16:17], v13 offset0:138 offset1:203
	v_add_u32_e32 v13, 0xc00, v11
	ds_read2_b32 v[18:19], v13 offset0:12 offset1:77
	ds_read2_b32 v[20:21], v13 offset0:142 offset1:207
	s_waitcnt lgkmcnt(6)
	v_and_b32_sdwa v13, v2, v232 dst_sel:DWORD dst_unused:UNUSED_PAD src0_sel:WORD_1 src1_sel:DWORD
	v_and_b32_sdwa v24, v0, v232 dst_sel:DWORD dst_unused:UNUSED_PAD src0_sel:WORD_1 src1_sel:DWORD
	v_add3_u32 v2, v2, v13, s69
	v_and_b32_sdwa v13, v3, v232 dst_sel:DWORD dst_unused:UNUSED_PAD src0_sel:WORD_1 src1_sel:DWORD
	v_add3_u32 v0, v0, v24, s69
	v_and_b32_sdwa v24, v1, v232 dst_sel:DWORD dst_unused:UNUSED_PAD src0_sel:WORD_1 src1_sel:DWORD
	v_add3_u32 v3, v3, v13, s69
	v_add3_u32 v1, v1, v24, s69
	v_and_b32_e32 v3, 0xffff0000, v3
	v_and_b32_e32 v13, 0xffff0000, v1
	v_or_b32_sdwa v1, v3, v2 dst_sel:DWORD dst_unused:UNUSED_PAD src0_sel:DWORD src1_sel:WORD_1
	s_waitcnt lgkmcnt(4)
	v_and_b32_sdwa v2, v6, v232 dst_sel:DWORD dst_unused:UNUSED_PAD src0_sel:WORD_1 src1_sel:DWORD
	v_and_b32_sdwa v3, v4, v232 dst_sel:DWORD dst_unused:UNUSED_PAD src0_sel:WORD_1 src1_sel:DWORD
	v_add3_u32 v4, v4, v3, s69
	v_add3_u32 v2, v6, v2, s69
	v_and_b32_sdwa v3, v7, v232 dst_sel:DWORD dst_unused:UNUSED_PAD src0_sel:WORD_1 src1_sel:DWORD
	v_and_b32_sdwa v6, v5, v232 dst_sel:DWORD dst_unused:UNUSED_PAD src0_sel:WORD_1 src1_sel:DWORD
	v_add3_u32 v3, v7, v3, s69
	v_add3_u32 v5, v5, v6, s69
	v_and_b32_e32 v3, 0xffff0000, v3
	v_and_b32_e32 v5, 0xffff0000, v5
	v_or_b32_sdwa v0, v13, v0 dst_sel:DWORD dst_unused:UNUSED_PAD src0_sel:DWORD src1_sel:WORD_1
	v_or_b32_sdwa v3, v3, v2 dst_sel:DWORD dst_unused:UNUSED_PAD src0_sel:DWORD src1_sel:WORD_1
	v_or_b32_sdwa v2, v5, v4 dst_sel:DWORD dst_unused:UNUSED_PAD src0_sel:DWORD src1_sel:WORD_1
	global_store_dwordx4 v[22:23], v[0:3], off
	s_waitcnt lgkmcnt(1)
	v_and_b32_sdwa v5, v19, v232 dst_sel:DWORD dst_unused:UNUSED_PAD src0_sel:WORD_1 src1_sel:DWORD
	v_add3_u32 v5, v19, v5, s69
	v_and_b32_sdwa v1, v14, v232 dst_sel:DWORD dst_unused:UNUSED_PAD src0_sel:WORD_1 src1_sel:DWORD
	v_add3_u32 v2, v14, v1, s69
	v_and_b32_sdwa v1, v17, v232 dst_sel:DWORD dst_unused:UNUSED_PAD src0_sel:WORD_1 src1_sel:DWORD
	v_and_b32_sdwa v3, v15, v232 dst_sel:DWORD dst_unused:UNUSED_PAD src0_sel:WORD_1 src1_sel:DWORD
	v_and_b32_sdwa v0, v16, v232 dst_sel:DWORD dst_unused:UNUSED_PAD src0_sel:WORD_1 src1_sel:DWORD
	v_add3_u32 v1, v17, v1, s69
	v_add3_u32 v3, v15, v3, s69
	v_add3_u32 v0, v16, v0, s69
	v_and_b32_e32 v1, 0xffff0000, v1
	v_and_b32_e32 v3, 0xffff0000, v3
	v_or_b32_sdwa v1, v1, v0 dst_sel:DWORD dst_unused:UNUSED_PAD src0_sel:DWORD src1_sel:WORD_1
	v_or_b32_sdwa v0, v3, v2 dst_sel:DWORD dst_unused:UNUSED_PAD src0_sel:DWORD src1_sel:WORD_1
	v_and_b32_sdwa v3, v18, v232 dst_sel:DWORD dst_unused:UNUSED_PAD src0_sel:WORD_1 src1_sel:DWORD
	v_add3_u32 v4, v18, v3, s69
	s_waitcnt lgkmcnt(0)
	v_and_b32_sdwa v3, v21, v232 dst_sel:DWORD dst_unused:UNUSED_PAD src0_sel:WORD_1 src1_sel:DWORD
	v_and_b32_sdwa v2, v20, v232 dst_sel:DWORD dst_unused:UNUSED_PAD src0_sel:WORD_1 src1_sel:DWORD
	v_add3_u32 v3, v21, v3, s69
	v_add3_u32 v2, v20, v2, s69
	v_and_b32_e32 v3, 0xffff0000, v3
	v_and_b32_e32 v5, 0xffff0000, v5
	v_or_b32_sdwa v3, v3, v2 dst_sel:DWORD dst_unused:UNUSED_PAD src0_sel:DWORD src1_sel:WORD_1
	v_or_b32_sdwa v2, v5, v4 dst_sel:DWORD dst_unused:UNUSED_PAD src0_sel:DWORD src1_sel:WORD_1
	global_store_dwordx4 v[22:23], v[0:3], off offset:16
	s_cbranch_scc1 .LBB0_38
	s_branch .LBB0_35

.LBB0_41:
	s_ashr_i32 s12, s14, 31
	s_lshr_b32 s12, s12, 28
	s_add_i32 s12, s14, s12
	s_ashr_i32 s13, s12, 4
	s_lshl_b32 s12, s13, 10
	s_sub_i32 s12, s15, s12
	s_lshl_b32 s13, s13, 6
	v_or_b32_e32 v0, s13, v8
	v_add_u32_e32 v2, s12, v9
	v_ashrrev_i32_e32 v1, 31, v0
	v_ashrrev_i32_e32 v3, 31, v2
	v_lshl_add_u64 v[0:1], v[0:1], 2, s[2:3]
	v_lshlrev_b64 v[4:5], 12, v[2:3]
	v_lshl_add_u64 v[4:5], v[0:1], 0, v[4:5]
	s_barrier
	global_load_dword v30, v[4:5], off
	v_add_u32_e32 v4, 4, v2
	v_ashrrev_i32_e32 v5, 31, v4
	v_lshlrev_b64 v[4:5], 12, v[4:5]
	v_lshl_add_u64 v[4:5], v[0:1], 0, v[4:5]
	v_add_u32_e32 v6, 0x400, v11
	v_add_u32_e32 v13, 0x800, v11
	v_add_u32_e32 v22, s13, v10
	v_ashrrev_i32_e32 v23, 31, v22
	v_lshlrev_b64 v[22:23], 11, v[22:23]
	v_lshl_add_u64 v[22:23], s[20:21], 0, v[22:23]
	s_ashr_i32 s13, s12, 31
	v_lshl_add_u64 v[22:23], s[12:13], 1, v[22:23]
	v_lshl_add_u64 v[22:23], v[22:23], 0, v[200:201]
	s_add_i32 s14, s14, s33
	s_add_i32 s15, s15, s68
	s_cmpk_lt_i32 s14, 0x100
	global_load_dword v31, v[4:5], off
	v_add_u32_e32 v4, 8, v2
	v_ashrrev_i32_e32 v5, 31, v4
	v_lshlrev_b64 v[4:5], 12, v[4:5]
	v_lshl_add_u64 v[4:5], v[0:1], 0, v[4:5]
	global_load_dword v32, v[4:5], off
	v_add_u32_e32 v4, 12, v2
	v_ashrrev_i32_e32 v5, 31, v4
	v_lshlrev_b64 v[4:5], 12, v[4:5]
	v_lshl_add_u64 v[4:5], v[0:1], 0, v[4:5]
	global_load_dword v33, v[4:5], off
	v_add_u32_e32 v4, 16, v2
	v_ashrrev_i32_e32 v5, 31, v4
	v_lshlrev_b64 v[4:5], 12, v[4:5]
	v_lshl_add_u64 v[4:5], v[0:1], 0, v[4:5]
	global_load_dword v34, v[4:5], off
	v_add_u32_e32 v4, 20, v2
	v_ashrrev_i32_e32 v5, 31, v4
	v_lshlrev_b64 v[4:5], 12, v[4:5]
	v_lshl_add_u64 v[4:5], v[0:1], 0, v[4:5]
	global_load_dword v35, v[4:5], off
	v_add_u32_e32 v4, 24, v2
	v_ashrrev_i32_e32 v5, 31, v4
	v_lshlrev_b64 v[4:5], 12, v[4:5]
	v_lshl_add_u64 v[4:5], v[0:1], 0, v[4:5]
	global_load_dword v36, v[4:5], off
	v_add_u32_e32 v4, 28, v2
	v_ashrrev_i32_e32 v5, 31, v4
	v_lshlrev_b64 v[4:5], 12, v[4:5]
	v_lshl_add_u64 v[4:5], v[0:1], 0, v[4:5]
	global_load_dword v37, v[4:5], off
	v_add_u32_e32 v4, 32, v2
	v_ashrrev_i32_e32 v5, 31, v4
	v_lshlrev_b64 v[4:5], 12, v[4:5]
	v_lshl_add_u64 v[4:5], v[0:1], 0, v[4:5]
	global_load_dword v38, v[4:5], off
	v_add_u32_e32 v4, 36, v2
	v_ashrrev_i32_e32 v5, 31, v4
	v_lshlrev_b64 v[4:5], 12, v[4:5]
	v_lshl_add_u64 v[4:5], v[0:1], 0, v[4:5]
	global_load_dword v39, v[4:5], off
	v_add_u32_e32 v4, 40, v2
	v_ashrrev_i32_e32 v5, 31, v4
	v_lshlrev_b64 v[4:5], 12, v[4:5]
	v_lshl_add_u64 v[4:5], v[0:1], 0, v[4:5]
	global_load_dword v40, v[4:5], off
	v_add_u32_e32 v4, 44, v2
	v_ashrrev_i32_e32 v5, 31, v4
	v_lshlrev_b64 v[4:5], 12, v[4:5]
	v_lshl_add_u64 v[4:5], v[0:1], 0, v[4:5]
	global_load_dword v41, v[4:5], off
	v_add_u32_e32 v4, 48, v2
	v_ashrrev_i32_e32 v5, 31, v4
	v_lshlrev_b64 v[4:5], 12, v[4:5]
	v_lshl_add_u64 v[4:5], v[0:1], 0, v[4:5]
	global_load_dword v42, v[4:5], off
	v_add_u32_e32 v4, 52, v2
	v_ashrrev_i32_e32 v5, 31, v4
	v_lshlrev_b64 v[4:5], 12, v[4:5]
	v_lshl_add_u64 v[4:5], v[0:1], 0, v[4:5]
	global_load_dword v43, v[4:5], off
	v_add_u32_e32 v4, 56, v2
	v_ashrrev_i32_e32 v5, 31, v4
	v_lshlrev_b64 v[4:5], 12, v[4:5]
	v_lshl_add_u64 v[4:5], v[0:1], 0, v[4:5]
	v_add_u32_e32 v2, 60, v2
	global_load_dword v44, v[4:5], off
	v_ashrrev_i32_e32 v3, 31, v2
	v_lshlrev_b64 v[2:3], 12, v[2:3]
	v_lshl_add_u64 v[0:1], v[0:1], 0, v[2:3]
	global_load_dword v45, v[0:1], off
	s_waitcnt vmcnt(15)
	ds_write_b32 v12, v30
	s_waitcnt vmcnt(14)
	ds_write_b32 v12, v31 offset:1040
	s_waitcnt vmcnt(13)
	ds_write_b32 v12, v32 offset:2080
	s_waitcnt vmcnt(12)
	ds_write_b32 v12, v33 offset:3120
	s_waitcnt vmcnt(11)
	ds_write_b32 v12, v34 offset:4160
	s_waitcnt vmcnt(10)
	ds_write_b32 v12, v35 offset:5200
	s_waitcnt vmcnt(9)
	ds_write_b32 v12, v36 offset:6240
	s_waitcnt vmcnt(8)
	ds_write_b32 v12, v37 offset:7280
	s_waitcnt vmcnt(7)
	ds_write_b32 v12, v38 offset:8320
	s_waitcnt vmcnt(6)
	ds_write_b32 v12, v39 offset:9360
	s_waitcnt vmcnt(5)
	ds_write_b32 v12, v40 offset:10400
	s_waitcnt vmcnt(4)
	ds_write_b32 v12, v41 offset:11440
	s_waitcnt vmcnt(3)
	ds_write_b32 v12, v42 offset:12480
	s_waitcnt vmcnt(2)
	ds_write_b32 v12, v43 offset:13520
	s_waitcnt vmcnt(1)
	ds_write_b32 v12, v44 offset:14560
	s_waitcnt vmcnt(0)
	ds_write_b32 v12, v45 offset:15600
	s_waitcnt lgkmcnt(0)
	s_barrier
	ds_read2_b32 v[0:1], v11 offset1:65
	ds_read2_b32 v[2:3], v11 offset0:130 offset1:195
	ds_read2_b32 v[4:5], v6 offset0:4 offset1:69
	ds_read2_b32 v[6:7], v6 offset0:134 offset1:199
	ds_read2_b32 v[14:15], v13 offset0:8 offset1:73
	ds_read2_b32 v[16:17], v13 offset0:138 offset1:203
	v_add_u32_e32 v13, 0xc00, v11
	ds_read2_b32 v[18:19], v13 offset0:12 offset1:77
	ds_read2_b32 v[20:21], v13 offset0:142 offset1:207
	s_waitcnt lgkmcnt(6)
	v_and_b32_sdwa v13, v2, v232 dst_sel:DWORD dst_unused:UNUSED_PAD src0_sel:WORD_1 src1_sel:DWORD
	v_and_b32_sdwa v24, v0, v232 dst_sel:DWORD dst_unused:UNUSED_PAD src0_sel:WORD_1 src1_sel:DWORD
	v_add3_u32 v2, v2, v13, s69
	v_and_b32_sdwa v13, v3, v232 dst_sel:DWORD dst_unused:UNUSED_PAD src0_sel:WORD_1 src1_sel:DWORD
	v_add3_u32 v0, v0, v24, s69
	v_and_b32_sdwa v24, v1, v232 dst_sel:DWORD dst_unused:UNUSED_PAD src0_sel:WORD_1 src1_sel:DWORD
	v_add3_u32 v3, v3, v13, s69
	v_add3_u32 v1, v1, v24, s69
	v_and_b32_e32 v3, 0xffff0000, v3
	v_and_b32_e32 v13, 0xffff0000, v1
	v_or_b32_sdwa v1, v3, v2 dst_sel:DWORD dst_unused:UNUSED_PAD src0_sel:DWORD src1_sel:WORD_1
	s_waitcnt lgkmcnt(4)
	v_and_b32_sdwa v2, v6, v232 dst_sel:DWORD dst_unused:UNUSED_PAD src0_sel:WORD_1 src1_sel:DWORD
	v_and_b32_sdwa v3, v4, v232 dst_sel:DWORD dst_unused:UNUSED_PAD src0_sel:WORD_1 src1_sel:DWORD
	v_add3_u32 v4, v4, v3, s69
	v_add3_u32 v2, v6, v2, s69
	v_and_b32_sdwa v3, v7, v232 dst_sel:DWORD dst_unused:UNUSED_PAD src0_sel:WORD_1 src1_sel:DWORD
	v_and_b32_sdwa v6, v5, v232 dst_sel:DWORD dst_unused:UNUSED_PAD src0_sel:WORD_1 src1_sel:DWORD
	v_add3_u32 v3, v7, v3, s69
	v_add3_u32 v5, v5, v6, s69
	v_and_b32_e32 v3, 0xffff0000, v3
	v_and_b32_e32 v5, 0xffff0000, v5
	v_or_b32_sdwa v0, v13, v0 dst_sel:DWORD dst_unused:UNUSED_PAD src0_sel:DWORD src1_sel:WORD_1
	v_or_b32_sdwa v3, v3, v2 dst_sel:DWORD dst_unused:UNUSED_PAD src0_sel:DWORD src1_sel:WORD_1
	v_or_b32_sdwa v2, v5, v4 dst_sel:DWORD dst_unused:UNUSED_PAD src0_sel:DWORD src1_sel:WORD_1
	global_store_dwordx4 v[22:23], v[0:3], off
	s_waitcnt lgkmcnt(1)
	v_and_b32_sdwa v5, v19, v232 dst_sel:DWORD dst_unused:UNUSED_PAD src0_sel:WORD_1 src1_sel:DWORD
	v_add3_u32 v5, v19, v5, s69
	v_and_b32_sdwa v1, v14, v232 dst_sel:DWORD dst_unused:UNUSED_PAD src0_sel:WORD_1 src1_sel:DWORD
	v_add3_u32 v2, v14, v1, s69
	v_and_b32_sdwa v1, v17, v232 dst_sel:DWORD dst_unused:UNUSED_PAD src0_sel:WORD_1 src1_sel:DWORD
	v_and_b32_sdwa v3, v15, v232 dst_sel:DWORD dst_unused:UNUSED_PAD src0_sel:WORD_1 src1_sel:DWORD
	v_and_b32_sdwa v0, v16, v232 dst_sel:DWORD dst_unused:UNUSED_PAD src0_sel:WORD_1 src1_sel:DWORD
	v_add3_u32 v1, v17, v1, s69
	v_add3_u32 v3, v15, v3, s69
	v_add3_u32 v0, v16, v0, s69
	v_and_b32_e32 v1, 0xffff0000, v1
	v_and_b32_e32 v3, 0xffff0000, v3
	v_or_b32_sdwa v1, v1, v0 dst_sel:DWORD dst_unused:UNUSED_PAD src0_sel:DWORD src1_sel:WORD_1
	v_or_b32_sdwa v0, v3, v2 dst_sel:DWORD dst_unused:UNUSED_PAD src0_sel:DWORD src1_sel:WORD_1
	v_and_b32_sdwa v3, v18, v232 dst_sel:DWORD dst_unused:UNUSED_PAD src0_sel:WORD_1 src1_sel:DWORD
	v_add3_u32 v4, v18, v3, s69
	s_waitcnt lgkmcnt(0)
	v_and_b32_sdwa v3, v21, v232 dst_sel:DWORD dst_unused:UNUSED_PAD src0_sel:WORD_1 src1_sel:DWORD
	v_and_b32_sdwa v2, v20, v232 dst_sel:DWORD dst_unused:UNUSED_PAD src0_sel:WORD_1 src1_sel:DWORD
	v_add3_u32 v3, v21, v3, s69
	v_add3_u32 v2, v20, v2, s69
	v_and_b32_e32 v3, 0xffff0000, v3
	v_and_b32_e32 v5, 0xffff0000, v5
	v_or_b32_sdwa v3, v3, v2 dst_sel:DWORD dst_unused:UNUSED_PAD src0_sel:DWORD src1_sel:WORD_1
	v_or_b32_sdwa v2, v5, v4 dst_sel:DWORD dst_unused:UNUSED_PAD src0_sel:DWORD src1_sel:WORD_1
	global_store_dwordx4 v[22:23], v[0:3], off offset:16
	s_cbranch_scc1 .LBB0_41

.LBB0_44:
	s_ashr_i32 s12, s15, 31
	s_lshr_b32 s12, s12, 30
	s_add_i32 s12, s15, s12
	s_ashr_i32 s17, s12, 2
	s_lshl_b32 s12, s17, 8
	s_lshl_b32 s13, s17, 6
	s_lshl_b32 s17, s17, 5
	v_or_b32_e32 v0, s13, v8
	s_andn2_b32 s17, s17, 63
	s_sub_i32 s12, s16, s12
	v_lshrrev_b32_e32 v0, 1, v0
	v_add_u32_e32 v1, s17, v12
	v_and_or_b32 v0, v0, 48, v1
	v_add_u32_e32 v2, s12, v9
	v_ashrrev_i32_e32 v1, 31, v0
	v_ashrrev_i32_e32 v3, 31, v2
	v_lshl_add_u64 v[0:1], v[0:1], 2, s[2:3]
	v_lshlrev_b64 v[4:5], 11, v[2:3]
	v_lshl_add_u64 v[4:5], v[0:1], 0, v[4:5]
	s_barrier
	global_load_dword v30, v[4:5], off
	v_add_u32_e32 v4, 4, v2
	v_ashrrev_i32_e32 v5, 31, v4
	v_lshlrev_b64 v[4:5], 11, v[4:5]
	v_lshl_add_u64 v[4:5], v[0:1], 0, v[4:5]
	v_add_u32_e32 v6, 0x400, v11
	v_add_u32_e32 v22, s13, v10
	v_add_u32_e32 v16, 0x800, v11
	v_ashrrev_i32_e32 v23, 31, v22
	v_lshlrev_b64 v[22:23], 9, v[22:23]
	v_lshl_add_u64 v[22:23], s[20:21], 0, v[22:23]
	s_ashr_i32 s13, s12, 31
	v_lshl_add_u64 v[22:23], s[12:13], 1, v[22:23]
	v_add_u32_e32 v20, 0xc00, v11
	v_lshl_add_u64 v[22:23], v[22:23], 0, v[200:201]
	s_add_i32 s15, s15, s33
	s_add_i32 s16, s16, s68
	s_cmp_lt_i32 s15, 32
	global_load_dword v31, v[4:5], off
	v_add_u32_e32 v4, 8, v2
	v_ashrrev_i32_e32 v5, 31, v4
	v_lshlrev_b64 v[4:5], 11, v[4:5]
	v_lshl_add_u64 v[4:5], v[0:1], 0, v[4:5]
	global_load_dword v32, v[4:5], off
	v_add_u32_e32 v4, 12, v2
	v_ashrrev_i32_e32 v5, 31, v4
	v_lshlrev_b64 v[4:5], 11, v[4:5]
	v_lshl_add_u64 v[4:5], v[0:1], 0, v[4:5]
	global_load_dword v33, v[4:5], off
	v_add_u32_e32 v4, 16, v2
	v_ashrrev_i32_e32 v5, 31, v4
	v_lshlrev_b64 v[4:5], 11, v[4:5]
	v_lshl_add_u64 v[4:5], v[0:1], 0, v[4:5]
	global_load_dword v34, v[4:5], off
	v_add_u32_e32 v4, 20, v2
	v_ashrrev_i32_e32 v5, 31, v4
	v_lshlrev_b64 v[4:5], 11, v[4:5]
	v_lshl_add_u64 v[4:5], v[0:1], 0, v[4:5]
	global_load_dword v35, v[4:5], off
	v_add_u32_e32 v4, 24, v2
	v_ashrrev_i32_e32 v5, 31, v4
	v_lshlrev_b64 v[4:5], 11, v[4:5]
	v_lshl_add_u64 v[4:5], v[0:1], 0, v[4:5]
	global_load_dword v36, v[4:5], off
	v_add_u32_e32 v4, 28, v2
	v_ashrrev_i32_e32 v5, 31, v4
	v_lshlrev_b64 v[4:5], 11, v[4:5]
	v_lshl_add_u64 v[4:5], v[0:1], 0, v[4:5]
	global_load_dword v37, v[4:5], off
	v_add_u32_e32 v4, 32, v2
	v_ashrrev_i32_e32 v5, 31, v4
	v_lshlrev_b64 v[4:5], 11, v[4:5]
	v_lshl_add_u64 v[4:5], v[0:1], 0, v[4:5]
	global_load_dword v38, v[4:5], off
	v_add_u32_e32 v4, 36, v2
	v_ashrrev_i32_e32 v5, 31, v4
	v_lshlrev_b64 v[4:5], 11, v[4:5]
	v_lshl_add_u64 v[4:5], v[0:1], 0, v[4:5]
	global_load_dword v39, v[4:5], off
	v_add_u32_e32 v4, 40, v2
	v_ashrrev_i32_e32 v5, 31, v4
	v_lshlrev_b64 v[4:5], 11, v[4:5]
	v_lshl_add_u64 v[4:5], v[0:1], 0, v[4:5]
	global_load_dword v40, v[4:5], off
	v_add_u32_e32 v4, 44, v2
	v_ashrrev_i32_e32 v5, 31, v4
	v_lshlrev_b64 v[4:5], 11, v[4:5]
	v_lshl_add_u64 v[4:5], v[0:1], 0, v[4:5]
	global_load_dword v41, v[4:5], off
	v_add_u32_e32 v4, 48, v2
	v_ashrrev_i32_e32 v5, 31, v4
	v_lshlrev_b64 v[4:5], 11, v[4:5]
	v_lshl_add_u64 v[4:5], v[0:1], 0, v[4:5]
	global_load_dword v42, v[4:5], off
	v_add_u32_e32 v4, 52, v2
	v_ashrrev_i32_e32 v5, 31, v4
	v_lshlrev_b64 v[4:5], 11, v[4:5]
	v_lshl_add_u64 v[4:5], v[0:1], 0, v[4:5]
	global_load_dword v43, v[4:5], off
	v_add_u32_e32 v4, 56, v2
	v_ashrrev_i32_e32 v5, 31, v4
	v_lshlrev_b64 v[4:5], 11, v[4:5]
	v_lshl_add_u64 v[4:5], v[0:1], 0, v[4:5]
	v_add_u32_e32 v2, 60, v2
	global_load_dword v44, v[4:5], off
	v_ashrrev_i32_e32 v3, 31, v2
	v_lshlrev_b64 v[2:3], 11, v[2:3]
	v_lshl_add_u64 v[0:1], v[0:1], 0, v[2:3]
	global_load_dword v45, v[0:1], off
	s_waitcnt vmcnt(15)
	ds_write_b32 v13, v30
	s_waitcnt vmcnt(14)
	ds_write_b32 v13, v31 offset:1040
	s_waitcnt vmcnt(13)
	ds_write_b32 v13, v32 offset:2080
	s_waitcnt vmcnt(12)
	ds_write_b32 v13, v33 offset:3120
	s_waitcnt vmcnt(11)
	ds_write_b32 v13, v34 offset:4160
	s_waitcnt vmcnt(10)
	ds_write_b32 v13, v35 offset:5200
	s_waitcnt vmcnt(9)
	ds_write_b32 v13, v36 offset:6240
	s_waitcnt vmcnt(8)
	ds_write_b32 v13, v37 offset:7280
	s_waitcnt vmcnt(7)
	ds_write_b32 v13, v38 offset:8320
	s_waitcnt vmcnt(6)
	ds_write_b32 v13, v39 offset:9360
	s_waitcnt vmcnt(5)
	ds_write_b32 v13, v40 offset:10400
	s_waitcnt vmcnt(4)
	ds_write_b32 v13, v41 offset:11440
	s_waitcnt vmcnt(3)
	ds_write_b32 v13, v42 offset:12480
	s_waitcnt vmcnt(2)
	ds_write_b32 v13, v43 offset:13520
	s_waitcnt vmcnt(1)
	ds_write_b32 v13, v44 offset:14560
	s_waitcnt vmcnt(0)
	ds_write_b32 v13, v45 offset:15600
	s_waitcnt lgkmcnt(0)
	s_barrier
	ds_read2_b32 v[0:1], v11 offset1:65
	ds_read2_b32 v[2:3], v11 offset0:130 offset1:195
	ds_read2_b32 v[4:5], v6 offset0:4 offset1:69
	ds_read2_b32 v[6:7], v6 offset0:134 offset1:199
	ds_read2_b32 v[14:15], v16 offset0:8 offset1:73
	ds_read2_b32 v[16:17], v16 offset0:138 offset1:203
	ds_read2_b32 v[18:19], v20 offset0:12 offset1:77
	ds_read2_b32 v[20:21], v20 offset0:142 offset1:207
	s_waitcnt lgkmcnt(7)
	v_and_b32_sdwa v25, v0, v232 dst_sel:DWORD dst_unused:UNUSED_PAD src0_sel:WORD_1 src1_sel:DWORD
	s_waitcnt lgkmcnt(6)
	v_and_b32_sdwa v24, v2, v232 dst_sel:DWORD dst_unused:UNUSED_PAD src0_sel:WORD_1 src1_sel:DWORD
	v_add3_u32 v2, v2, v24, s69
	v_and_b32_sdwa v24, v3, v232 dst_sel:DWORD dst_unused:UNUSED_PAD src0_sel:WORD_1 src1_sel:DWORD
	v_add3_u32 v0, v0, v25, s69
	v_and_b32_sdwa v25, v1, v232 dst_sel:DWORD dst_unused:UNUSED_PAD src0_sel:WORD_1 src1_sel:DWORD
	v_add3_u32 v3, v3, v24, s69
	v_add3_u32 v1, v1, v25, s69
	v_and_b32_e32 v3, 0xffff0000, v3
	v_and_b32_e32 v24, 0xffff0000, v1
	v_or_b32_sdwa v1, v3, v2 dst_sel:DWORD dst_unused:UNUSED_PAD src0_sel:DWORD src1_sel:WORD_1
	s_waitcnt lgkmcnt(4)
	v_and_b32_sdwa v2, v6, v232 dst_sel:DWORD dst_unused:UNUSED_PAD src0_sel:WORD_1 src1_sel:DWORD
	v_and_b32_sdwa v3, v4, v232 dst_sel:DWORD dst_unused:UNUSED_PAD src0_sel:WORD_1 src1_sel:DWORD
	v_add3_u32 v4, v4, v3, s69
	v_add3_u32 v2, v6, v2, s69
	v_and_b32_sdwa v3, v7, v232 dst_sel:DWORD dst_unused:UNUSED_PAD src0_sel:WORD_1 src1_sel:DWORD
	v_and_b32_sdwa v6, v5, v232 dst_sel:DWORD dst_unused:UNUSED_PAD src0_sel:WORD_1 src1_sel:DWORD
	v_add3_u32 v3, v7, v3, s69
	v_add3_u32 v5, v5, v6, s69
	v_and_b32_e32 v3, 0xffff0000, v3
	v_and_b32_e32 v5, 0xffff0000, v5
	v_or_b32_sdwa v0, v24, v0 dst_sel:DWORD dst_unused:UNUSED_PAD src0_sel:DWORD src1_sel:WORD_1
	v_or_b32_sdwa v3, v3, v2 dst_sel:DWORD dst_unused:UNUSED_PAD src0_sel:DWORD src1_sel:WORD_1
	v_or_b32_sdwa v2, v5, v4 dst_sel:DWORD dst_unused:UNUSED_PAD src0_sel:DWORD src1_sel:WORD_1
	global_store_dwordx4 v[22:23], v[0:3], off
	s_waitcnt lgkmcnt(1)
	v_and_b32_sdwa v5, v19, v232 dst_sel:DWORD dst_unused:UNUSED_PAD src0_sel:WORD_1 src1_sel:DWORD
	v_add3_u32 v5, v19, v5, s69
	v_and_b32_sdwa v1, v14, v232 dst_sel:DWORD dst_unused:UNUSED_PAD src0_sel:WORD_1 src1_sel:DWORD
	v_add3_u32 v2, v14, v1, s69
	v_and_b32_sdwa v1, v17, v232 dst_sel:DWORD dst_unused:UNUSED_PAD src0_sel:WORD_1 src1_sel:DWORD
	v_and_b32_sdwa v3, v15, v232 dst_sel:DWORD dst_unused:UNUSED_PAD src0_sel:WORD_1 src1_sel:DWORD
	v_and_b32_sdwa v0, v16, v232 dst_sel:DWORD dst_unused:UNUSED_PAD src0_sel:WORD_1 src1_sel:DWORD
	v_add3_u32 v1, v17, v1, s69
	v_add3_u32 v3, v15, v3, s69
	v_add3_u32 v0, v16, v0, s69
	v_and_b32_e32 v1, 0xffff0000, v1
	v_and_b32_e32 v3, 0xffff0000, v3
	v_or_b32_sdwa v1, v1, v0 dst_sel:DWORD dst_unused:UNUSED_PAD src0_sel:DWORD src1_sel:WORD_1
	v_or_b32_sdwa v0, v3, v2 dst_sel:DWORD dst_unused:UNUSED_PAD src0_sel:DWORD src1_sel:WORD_1
	v_and_b32_sdwa v3, v18, v232 dst_sel:DWORD dst_unused:UNUSED_PAD src0_sel:WORD_1 src1_sel:DWORD
	v_add3_u32 v4, v18, v3, s69
	s_waitcnt lgkmcnt(0)
	v_and_b32_sdwa v3, v21, v232 dst_sel:DWORD dst_unused:UNUSED_PAD src0_sel:WORD_1 src1_sel:DWORD
	v_and_b32_sdwa v2, v20, v232 dst_sel:DWORD dst_unused:UNUSED_PAD src0_sel:WORD_1 src1_sel:DWORD
	v_add3_u32 v3, v21, v3, s69
	v_add3_u32 v2, v20, v2, s69
	v_and_b32_e32 v3, 0xffff0000, v3
	v_and_b32_e32 v5, 0xffff0000, v5
	v_or_b32_sdwa v3, v3, v2 dst_sel:DWORD dst_unused:UNUSED_PAD src0_sel:DWORD src1_sel:WORD_1
	v_or_b32_sdwa v2, v5, v4 dst_sel:DWORD dst_unused:UNUSED_PAD src0_sel:DWORD src1_sel:WORD_1
	global_store_dwordx4 v[22:23], v[0:3], off offset:16
	s_cbranch_scc1 .LBB0_44
	v_readlane_b32 s34, v253, 2
	v_readlane_b32 s52, v253, 9
	v_readlane_b32 s35, v253, 3
	v_readlane_b32 s53, v253, 10
	v_readlane_b32 s30, v255, 20
	v_readlane_b32 s31, v255, 21
	v_readlane_b32 s54, v255, 12
	v_readlane_b32 s56, v255, 10
	v_readlane_b32 s55, v255, 13
	v_readlane_b32 s57, v255, 11

.LBB0_48:
	s_ashr_i32 s10, s13, 31
	s_lshr_b32 s10, s10, 28
	s_add_i32 s10, s13, s10
	s_ashr_i32 s15, s10, 4
	s_lshl_b32 s10, s15, 10
	s_lshl_b32 s11, s15, 6
	s_lshl_b32 s15, s15, 5
	v_or_b32_e32 v0, s11, v4
	s_andn2_b32 s15, s15, 63
	v_lshrrev_b32_e32 v0, 1, v0
	v_add_u32_e32 v1, s15, v8
	v_and_or_b32 v0, v0, 48, v1
	s_sub_i32 s10, s14, s10
	v_ashrrev_i32_e32 v1, 31, v0
	v_lshl_add_u64 v[0:1], v[0:1], 2, s[2:3]
	v_add_u32_e32 v10, s10, v5
	v_mad_i64_i32 v[2:3], s[16:17], v10, s74, v[0:1]
	s_barrier
	global_load_dword v30, v[2:3], off
	v_add_u32_e32 v12, 0x400, v7
	v_add_u32_e32 v22, s11, v6
	v_add_u32_e32 v16, 0x800, v7
	v_ashrrev_i32_e32 v23, 31, v22
	v_lshlrev_b64 v[22:23], 11, v[22:23]
	v_lshl_add_u64 v[22:23], s[20:21], 0, v[22:23]
	s_ashr_i32 s11, s10, 31
	v_lshl_add_u64 v[22:23], s[10:11], 1, v[22:23]
	v_add_u32_e32 v20, 0xc00, v7
	v_lshl_add_u64 v[22:23], v[22:23], 0, v[200:201]
	s_add_i32 s13, s13, s33
	s_add_i32 s14, s14, s68
	s_cmpk_lt_i32 s13, 0x580
	v_add_u32_e32 v2, 4, v10
	v_mad_i64_i32 v[2:3], s[16:17], v2, s74, v[0:1]
	global_load_dword v31, v[2:3], off
	v_add_u32_e32 v2, 8, v10
	v_mad_i64_i32 v[2:3], s[16:17], v2, s74, v[0:1]
	global_load_dword v32, v[2:3], off
	v_add_u32_e32 v2, 12, v10
	v_mad_i64_i32 v[2:3], s[16:17], v2, s74, v[0:1]
	global_load_dword v33, v[2:3], off
	v_add_u32_e32 v2, 16, v10
	v_mad_i64_i32 v[2:3], s[16:17], v2, s74, v[0:1]
	global_load_dword v34, v[2:3], off
	v_add_u32_e32 v2, 20, v10
	v_mad_i64_i32 v[2:3], s[16:17], v2, s74, v[0:1]
	global_load_dword v35, v[2:3], off
	v_add_u32_e32 v2, 24, v10
	v_mad_i64_i32 v[2:3], s[16:17], v2, s74, v[0:1]
	global_load_dword v36, v[2:3], off
	v_add_u32_e32 v2, 28, v10
	v_mad_i64_i32 v[2:3], s[16:17], v2, s74, v[0:1]
	global_load_dword v37, v[2:3], off
	v_add_u32_e32 v2, 32, v10
	v_mad_i64_i32 v[2:3], s[16:17], v2, s74, v[0:1]
	global_load_dword v38, v[2:3], off
	v_add_u32_e32 v2, 36, v10
	v_mad_i64_i32 v[2:3], s[16:17], v2, s74, v[0:1]
	global_load_dword v39, v[2:3], off
	v_add_u32_e32 v2, 40, v10
	v_mad_i64_i32 v[2:3], s[16:17], v2, s74, v[0:1]
	global_load_dword v40, v[2:3], off
	v_add_u32_e32 v2, 44, v10
	v_mad_i64_i32 v[2:3], s[16:17], v2, s74, v[0:1]
	global_load_dword v41, v[2:3], off
	v_add_u32_e32 v2, 48, v10
	v_mad_i64_i32 v[2:3], s[16:17], v2, s74, v[0:1]
	global_load_dword v42, v[2:3], off
	v_add_u32_e32 v2, 52, v10
	v_mad_i64_i32 v[2:3], s[16:17], v2, s74, v[0:1]
	global_load_dword v43, v[2:3], off
	v_add_u32_e32 v2, 56, v10
	v_mad_i64_i32 v[2:3], s[16:17], v2, s74, v[0:1]
	global_load_dword v44, v[2:3], off
	v_add_u32_e32 v2, 60, v10
	v_mad_i64_i32 v[0:1], s[16:17], v2, s74, v[0:1]
	global_load_dword v45, v[0:1], off
	s_waitcnt vmcnt(15)
	ds_write_b32 v9, v30
	s_waitcnt vmcnt(14)
	ds_write_b32 v9, v31 offset:1040
	s_waitcnt vmcnt(13)
	ds_write_b32 v9, v32 offset:2080
	s_waitcnt vmcnt(12)
	ds_write_b32 v9, v33 offset:3120
	s_waitcnt vmcnt(11)
	ds_write_b32 v9, v34 offset:4160
	s_waitcnt vmcnt(10)
	ds_write_b32 v9, v35 offset:5200
	s_waitcnt vmcnt(9)
	ds_write_b32 v9, v36 offset:6240
	s_waitcnt vmcnt(8)
	ds_write_b32 v9, v37 offset:7280
	s_waitcnt vmcnt(7)
	ds_write_b32 v9, v38 offset:8320
	s_waitcnt vmcnt(6)
	ds_write_b32 v9, v39 offset:9360
	s_waitcnt vmcnt(5)
	ds_write_b32 v9, v40 offset:10400
	s_waitcnt vmcnt(4)
	ds_write_b32 v9, v41 offset:11440
	s_waitcnt vmcnt(3)
	ds_write_b32 v9, v42 offset:12480
	s_waitcnt vmcnt(2)
	ds_write_b32 v9, v43 offset:13520
	s_waitcnt vmcnt(1)
	ds_write_b32 v9, v44 offset:14560
	s_waitcnt vmcnt(0)
	ds_write_b32 v9, v45 offset:15600
	s_waitcnt lgkmcnt(0)
	s_barrier
	ds_read2_b32 v[0:1], v7 offset1:65
	ds_read2_b32 v[2:3], v7 offset0:130 offset1:195
	ds_read2_b32 v[10:11], v12 offset0:4 offset1:69
	ds_read2_b32 v[12:13], v12 offset0:134 offset1:199
	ds_read2_b32 v[14:15], v16 offset0:8 offset1:73
	ds_read2_b32 v[16:17], v16 offset0:138 offset1:203
	ds_read2_b32 v[18:19], v20 offset0:12 offset1:77
	ds_read2_b32 v[20:21], v20 offset0:142 offset1:207
	s_waitcnt lgkmcnt(7)
	v_and_b32_sdwa v25, v0, v232 dst_sel:DWORD dst_unused:UNUSED_PAD src0_sel:WORD_1 src1_sel:DWORD
	s_waitcnt lgkmcnt(6)
	v_and_b32_sdwa v24, v2, v232 dst_sel:DWORD dst_unused:UNUSED_PAD src0_sel:WORD_1 src1_sel:DWORD
	v_add3_u32 v2, v2, v24, s69
	v_and_b32_sdwa v24, v3, v232 dst_sel:DWORD dst_unused:UNUSED_PAD src0_sel:WORD_1 src1_sel:DWORD
	v_add3_u32 v0, v0, v25, s69
	v_and_b32_sdwa v25, v1, v232 dst_sel:DWORD dst_unused:UNUSED_PAD src0_sel:WORD_1 src1_sel:DWORD
	v_add3_u32 v3, v3, v24, s69
	v_add3_u32 v1, v1, v25, s69
	v_and_b32_e32 v3, 0xffff0000, v3
	v_and_b32_e32 v24, 0xffff0000, v1
	v_or_b32_sdwa v1, v3, v2 dst_sel:DWORD dst_unused:UNUSED_PAD src0_sel:DWORD src1_sel:WORD_1
	s_waitcnt lgkmcnt(4)
	v_and_b32_sdwa v2, v12, v232 dst_sel:DWORD dst_unused:UNUSED_PAD src0_sel:WORD_1 src1_sel:DWORD
	v_and_b32_sdwa v3, v10, v232 dst_sel:DWORD dst_unused:UNUSED_PAD src0_sel:WORD_1 src1_sel:DWORD
	v_add3_u32 v10, v10, v3, s69
	v_add3_u32 v2, v12, v2, s69
	v_and_b32_sdwa v3, v13, v232 dst_sel:DWORD dst_unused:UNUSED_PAD src0_sel:WORD_1 src1_sel:DWORD
	v_and_b32_sdwa v12, v11, v232 dst_sel:DWORD dst_unused:UNUSED_PAD src0_sel:WORD_1 src1_sel:DWORD
	v_add3_u32 v3, v13, v3, s69
	v_add3_u32 v11, v11, v12, s69
	v_and_b32_e32 v3, 0xffff0000, v3
	v_and_b32_e32 v11, 0xffff0000, v11
	v_or_b32_sdwa v0, v24, v0 dst_sel:DWORD dst_unused:UNUSED_PAD src0_sel:DWORD src1_sel:WORD_1
	v_or_b32_sdwa v3, v3, v2 dst_sel:DWORD dst_unused:UNUSED_PAD src0_sel:DWORD src1_sel:WORD_1
	v_or_b32_sdwa v2, v11, v10 dst_sel:DWORD dst_unused:UNUSED_PAD src0_sel:DWORD src1_sel:WORD_1
	global_store_dwordx4 v[22:23], v[0:3], off
	s_waitcnt lgkmcnt(1)
	v_and_b32_sdwa v11, v19, v232 dst_sel:DWORD dst_unused:UNUSED_PAD src0_sel:WORD_1 src1_sel:DWORD
	v_add3_u32 v11, v19, v11, s69
	v_and_b32_sdwa v1, v14, v232 dst_sel:DWORD dst_unused:UNUSED_PAD src0_sel:WORD_1 src1_sel:DWORD
	v_add3_u32 v2, v14, v1, s69
	v_and_b32_sdwa v1, v17, v232 dst_sel:DWORD dst_unused:UNUSED_PAD src0_sel:WORD_1 src1_sel:DWORD
	v_and_b32_sdwa v3, v15, v232 dst_sel:DWORD dst_unused:UNUSED_PAD src0_sel:WORD_1 src1_sel:DWORD
	v_and_b32_sdwa v0, v16, v232 dst_sel:DWORD dst_unused:UNUSED_PAD src0_sel:WORD_1 src1_sel:DWORD
	v_add3_u32 v1, v17, v1, s69
	v_add3_u32 v3, v15, v3, s69
	v_add3_u32 v0, v16, v0, s69
	v_and_b32_e32 v1, 0xffff0000, v1
	v_and_b32_e32 v3, 0xffff0000, v3
	v_or_b32_sdwa v1, v1, v0 dst_sel:DWORD dst_unused:UNUSED_PAD src0_sel:DWORD src1_sel:WORD_1
	v_or_b32_sdwa v0, v3, v2 dst_sel:DWORD dst_unused:UNUSED_PAD src0_sel:DWORD src1_sel:WORD_1
	v_and_b32_sdwa v3, v18, v232 dst_sel:DWORD dst_unused:UNUSED_PAD src0_sel:WORD_1 src1_sel:DWORD
	v_add3_u32 v10, v18, v3, s69
	s_waitcnt lgkmcnt(0)
	v_and_b32_sdwa v3, v21, v232 dst_sel:DWORD dst_unused:UNUSED_PAD src0_sel:WORD_1 src1_sel:DWORD
	v_and_b32_sdwa v2, v20, v232 dst_sel:DWORD dst_unused:UNUSED_PAD src0_sel:WORD_1 src1_sel:DWORD
	v_add3_u32 v3, v21, v3, s69
	v_add3_u32 v2, v20, v2, s69
	v_and_b32_e32 v3, 0xffff0000, v3
	v_and_b32_e32 v11, 0xffff0000, v11
	v_or_b32_sdwa v3, v3, v2 dst_sel:DWORD dst_unused:UNUSED_PAD src0_sel:DWORD src1_sel:WORD_1
	v_or_b32_sdwa v2, v11, v10 dst_sel:DWORD dst_unused:UNUSED_PAD src0_sel:DWORD src1_sel:WORD_1
	global_store_dwordx4 v[22:23], v[0:3], off offset:16
	s_cbranch_scc1 .LBB0_48

.LBB0_51:
	s_mul_hi_i32 s4, s10, 0x2e8ba2e9
	s_lshr_b32 s5, s4, 31
	s_ashr_i32 s4, s4, 3
	s_add_i32 s5, s4, s5
	s_mul_i32 s4, s5, 0xfffff500
	s_add_i32 s4, s11, s4
	s_lshl_b32 s5, s5, 6
	v_or_b32_e32 v0, s5, v8
	v_add_u32_e32 v2, s4, v9
	v_ashrrev_i32_e32 v1, 31, v0
	v_ashrrev_i32_e32 v3, 31, v2
	v_lshl_add_u64 v[0:1], v[0:1], 2, s[2:3]
	v_lshlrev_b64 v[4:5], 12, v[2:3]
	v_lshl_add_u64 v[4:5], v[0:1], 0, v[4:5]
	s_barrier
	global_load_dword v30, v[4:5], off
	v_add_u32_e32 v4, 4, v2
	v_ashrrev_i32_e32 v5, 31, v4
	v_lshlrev_b64 v[4:5], 12, v[4:5]
	v_lshl_add_u64 v[4:5], v[0:1], 0, v[4:5]
	v_add_u32_e32 v6, 0x400, v11
	v_add_u32_e32 v13, 0x800, v11
	v_mov_b64_e32 v[22:23], s[14:15]
	s_add_i32 s10, s10, s33
	s_add_i32 s11, s11, s68
	global_load_dword v31, v[4:5], off
	v_add_u32_e32 v4, 8, v2
	v_ashrrev_i32_e32 v5, 31, v4
	v_lshlrev_b64 v[4:5], 12, v[4:5]
	v_lshl_add_u64 v[4:5], v[0:1], 0, v[4:5]
	global_load_dword v32, v[4:5], off
	v_add_u32_e32 v4, 12, v2
	v_ashrrev_i32_e32 v5, 31, v4
	v_lshlrev_b64 v[4:5], 12, v[4:5]
	v_lshl_add_u64 v[4:5], v[0:1], 0, v[4:5]
	global_load_dword v33, v[4:5], off
	v_add_u32_e32 v4, 16, v2
	v_ashrrev_i32_e32 v5, 31, v4
	v_lshlrev_b64 v[4:5], 12, v[4:5]
	v_lshl_add_u64 v[4:5], v[0:1], 0, v[4:5]
	global_load_dword v34, v[4:5], off
	v_add_u32_e32 v4, 20, v2
	v_ashrrev_i32_e32 v5, 31, v4
	v_lshlrev_b64 v[4:5], 12, v[4:5]
	v_lshl_add_u64 v[4:5], v[0:1], 0, v[4:5]
	global_load_dword v35, v[4:5], off
	v_add_u32_e32 v4, 24, v2
	v_ashrrev_i32_e32 v5, 31, v4
	v_lshlrev_b64 v[4:5], 12, v[4:5]
	v_lshl_add_u64 v[4:5], v[0:1], 0, v[4:5]
	global_load_dword v36, v[4:5], off
	v_add_u32_e32 v4, 28, v2
	v_ashrrev_i32_e32 v5, 31, v4
	v_lshlrev_b64 v[4:5], 12, v[4:5]
	v_lshl_add_u64 v[4:5], v[0:1], 0, v[4:5]
	global_load_dword v37, v[4:5], off
	v_add_u32_e32 v4, 32, v2
	v_ashrrev_i32_e32 v5, 31, v4
	v_lshlrev_b64 v[4:5], 12, v[4:5]
	v_lshl_add_u64 v[4:5], v[0:1], 0, v[4:5]
	global_load_dword v38, v[4:5], off
	v_add_u32_e32 v4, 36, v2
	v_ashrrev_i32_e32 v5, 31, v4
	v_lshlrev_b64 v[4:5], 12, v[4:5]
	v_lshl_add_u64 v[4:5], v[0:1], 0, v[4:5]
	global_load_dword v39, v[4:5], off
	v_add_u32_e32 v4, 40, v2
	v_ashrrev_i32_e32 v5, 31, v4
	v_lshlrev_b64 v[4:5], 12, v[4:5]
	v_lshl_add_u64 v[4:5], v[0:1], 0, v[4:5]
	global_load_dword v40, v[4:5], off
	v_add_u32_e32 v4, 44, v2
	v_ashrrev_i32_e32 v5, 31, v4
	v_lshlrev_b64 v[4:5], 12, v[4:5]
	v_lshl_add_u64 v[4:5], v[0:1], 0, v[4:5]
	global_load_dword v41, v[4:5], off
	v_add_u32_e32 v4, 48, v2
	v_ashrrev_i32_e32 v5, 31, v4
	v_lshlrev_b64 v[4:5], 12, v[4:5]
	v_lshl_add_u64 v[4:5], v[0:1], 0, v[4:5]
	global_load_dword v42, v[4:5], off
	v_add_u32_e32 v4, 52, v2
	v_ashrrev_i32_e32 v5, 31, v4
	v_lshlrev_b64 v[4:5], 12, v[4:5]
	v_lshl_add_u64 v[4:5], v[0:1], 0, v[4:5]
	global_load_dword v43, v[4:5], off
	v_add_u32_e32 v4, 56, v2
	v_ashrrev_i32_e32 v5, 31, v4
	v_lshlrev_b64 v[4:5], 12, v[4:5]
	v_lshl_add_u64 v[4:5], v[0:1], 0, v[4:5]
	v_add_u32_e32 v2, 60, v2
	global_load_dword v44, v[4:5], off
	v_ashrrev_i32_e32 v3, 31, v2
	v_lshlrev_b64 v[2:3], 12, v[2:3]
	v_lshl_add_u64 v[0:1], v[0:1], 0, v[2:3]
	global_load_dword v45, v[0:1], off
	s_waitcnt vmcnt(15)
	ds_write_b32 v12, v30
	s_waitcnt vmcnt(14)
	ds_write_b32 v12, v31 offset:1040
	s_waitcnt vmcnt(13)
	ds_write_b32 v12, v32 offset:2080
	s_waitcnt vmcnt(12)
	ds_write_b32 v12, v33 offset:3120
	s_waitcnt vmcnt(11)
	ds_write_b32 v12, v34 offset:4160
	s_waitcnt vmcnt(10)
	ds_write_b32 v12, v35 offset:5200
	s_waitcnt vmcnt(9)
	ds_write_b32 v12, v36 offset:6240
	s_waitcnt vmcnt(8)
	ds_write_b32 v12, v37 offset:7280
	s_waitcnt vmcnt(7)
	ds_write_b32 v12, v38 offset:8320
	s_waitcnt vmcnt(6)
	ds_write_b32 v12, v39 offset:9360
	s_waitcnt vmcnt(5)
	ds_write_b32 v12, v40 offset:10400
	s_waitcnt vmcnt(4)
	ds_write_b32 v12, v41 offset:11440
	s_waitcnt vmcnt(3)
	ds_write_b32 v12, v42 offset:12480
	s_waitcnt vmcnt(2)
	ds_write_b32 v12, v43 offset:13520
	s_waitcnt vmcnt(1)
	ds_write_b32 v12, v44 offset:14560
	s_waitcnt vmcnt(0)
	ds_write_b32 v12, v45 offset:15600
	s_waitcnt lgkmcnt(0)
	s_barrier
	ds_read2_b32 v[0:1], v11 offset1:65
	ds_read2_b32 v[2:3], v11 offset0:130 offset1:195
	ds_read2_b32 v[4:5], v6 offset0:4 offset1:69
	ds_read2_b32 v[6:7], v6 offset0:134 offset1:199
	ds_read2_b32 v[14:15], v13 offset0:8 offset1:73
	ds_read2_b32 v[16:17], v13 offset0:138 offset1:203
	v_add_u32_e32 v13, 0xc00, v11
	ds_read2_b32 v[18:19], v13 offset0:12 offset1:77
	ds_read2_b32 v[20:21], v13 offset0:142 offset1:207
	v_add_u32_e32 v13, s5, v10
	v_mad_i64_i32 v[22:23], s[12:13], v13, s16, v[22:23]
	s_waitcnt lgkmcnt(6)
	v_and_b32_sdwa v13, v2, v232 dst_sel:DWORD dst_unused:UNUSED_PAD src0_sel:WORD_1 src1_sel:DWORD
	v_and_b32_sdwa v24, v0, v232 dst_sel:DWORD dst_unused:UNUSED_PAD src0_sel:WORD_1 src1_sel:DWORD
	v_add3_u32 v2, v2, v13, s69
	v_and_b32_sdwa v13, v3, v232 dst_sel:DWORD dst_unused:UNUSED_PAD src0_sel:WORD_1 src1_sel:DWORD
	v_add3_u32 v0, v0, v24, s69
	v_and_b32_sdwa v24, v1, v232 dst_sel:DWORD dst_unused:UNUSED_PAD src0_sel:WORD_1 src1_sel:DWORD
	v_add3_u32 v3, v3, v13, s69
	v_add3_u32 v1, v1, v24, s69
	v_and_b32_e32 v3, 0xffff0000, v3
	v_and_b32_e32 v13, 0xffff0000, v1
	v_or_b32_sdwa v1, v3, v2 dst_sel:DWORD dst_unused:UNUSED_PAD src0_sel:DWORD src1_sel:WORD_1
	s_waitcnt lgkmcnt(4)
	v_and_b32_sdwa v2, v6, v232 dst_sel:DWORD dst_unused:UNUSED_PAD src0_sel:WORD_1 src1_sel:DWORD
	v_and_b32_sdwa v3, v4, v232 dst_sel:DWORD dst_unused:UNUSED_PAD src0_sel:WORD_1 src1_sel:DWORD
	v_add3_u32 v4, v4, v3, s69
	v_add3_u32 v2, v6, v2, s69
	v_and_b32_sdwa v3, v7, v232 dst_sel:DWORD dst_unused:UNUSED_PAD src0_sel:WORD_1 src1_sel:DWORD
	v_and_b32_sdwa v6, v5, v232 dst_sel:DWORD dst_unused:UNUSED_PAD src0_sel:WORD_1 src1_sel:DWORD
	s_ashr_i32 s5, s4, 31
	v_add3_u32 v3, v7, v3, s69
	v_add3_u32 v5, v5, v6, s69
	v_lshl_add_u64 v[22:23], s[4:5], 1, v[22:23]
	v_and_b32_e32 v3, 0xffff0000, v3
	v_and_b32_e32 v5, 0xffff0000, v5
	v_lshl_add_u64 v[22:23], v[22:23], 0, v[200:201]
	v_or_b32_sdwa v0, v13, v0 dst_sel:DWORD dst_unused:UNUSED_PAD src0_sel:DWORD src1_sel:WORD_1
	v_or_b32_sdwa v3, v3, v2 dst_sel:DWORD dst_unused:UNUSED_PAD src0_sel:DWORD src1_sel:WORD_1
	v_or_b32_sdwa v2, v5, v4 dst_sel:DWORD dst_unused:UNUSED_PAD src0_sel:DWORD src1_sel:WORD_1
	global_store_dwordx4 v[22:23], v[0:3], off
	s_waitcnt lgkmcnt(1)
	v_and_b32_sdwa v5, v19, v232 dst_sel:DWORD dst_unused:UNUSED_PAD src0_sel:WORD_1 src1_sel:DWORD
	v_add3_u32 v5, v19, v5, s69
	v_and_b32_sdwa v1, v14, v232 dst_sel:DWORD dst_unused:UNUSED_PAD src0_sel:WORD_1 src1_sel:DWORD
	v_add3_u32 v2, v14, v1, s69
	v_and_b32_sdwa v1, v17, v232 dst_sel:DWORD dst_unused:UNUSED_PAD src0_sel:WORD_1 src1_sel:DWORD
	v_and_b32_sdwa v3, v15, v232 dst_sel:DWORD dst_unused:UNUSED_PAD src0_sel:WORD_1 src1_sel:DWORD
	v_and_b32_sdwa v0, v16, v232 dst_sel:DWORD dst_unused:UNUSED_PAD src0_sel:WORD_1 src1_sel:DWORD
	v_add3_u32 v1, v17, v1, s69
	v_add3_u32 v3, v15, v3, s69
	v_add3_u32 v0, v16, v0, s69
	v_and_b32_e32 v1, 0xffff0000, v1
	v_and_b32_e32 v3, 0xffff0000, v3
	v_or_b32_sdwa v1, v1, v0 dst_sel:DWORD dst_unused:UNUSED_PAD src0_sel:DWORD src1_sel:WORD_1
	v_or_b32_sdwa v0, v3, v2 dst_sel:DWORD dst_unused:UNUSED_PAD src0_sel:DWORD src1_sel:WORD_1
	v_and_b32_sdwa v3, v18, v232 dst_sel:DWORD dst_unused:UNUSED_PAD src0_sel:WORD_1 src1_sel:DWORD
	v_add3_u32 v4, v18, v3, s69
	s_waitcnt lgkmcnt(0)
	v_and_b32_sdwa v3, v21, v232 dst_sel:DWORD dst_unused:UNUSED_PAD src0_sel:WORD_1 src1_sel:DWORD
	v_and_b32_sdwa v2, v20, v232 dst_sel:DWORD dst_unused:UNUSED_PAD src0_sel:WORD_1 src1_sel:DWORD
	v_add3_u32 v3, v21, v3, s69
	v_add3_u32 v2, v20, v2, s69
	v_and_b32_e32 v3, 0xffff0000, v3
	v_and_b32_e32 v5, 0xffff0000, v5
	v_or_b32_sdwa v3, v3, v2 dst_sel:DWORD dst_unused:UNUSED_PAD src0_sel:DWORD src1_sel:WORD_1
	v_or_b32_sdwa v2, v5, v4 dst_sel:DWORD dst_unused:UNUSED_PAD src0_sel:DWORD src1_sel:WORD_1
	s_cmpk_gt_i32 s10, 0x2bf
	global_store_dwordx4 v[22:23], v[0:3], off offset:16
	s_cbranch_scc0 .LBB0_51
